# GEMM loop: priorities swapped: load segments at s_setprio 1, MFMA segments at s_setprio 0
# baseline (speedup 1.0000x reference)
.LBB0_176:
	s_mov_b32 m0, s55
	s_nop 0
	global_load_lds_dwordx4 v194, s[100:101]
	s_mov_b32 m0, s67
	s_nop 0
	global_load_lds_dwordx4 v196, s[100:101]
	v_add_u32_e32 v130, 0x10000, v243
	v_add_u32_e32 v142, 0x14000, v243
	ds_read_b128 v[146:149], v130
	ds_read_b128 v[150:153], v130 offset:1024
	ds_read_b128 v[154:157], v130 offset:2048
	ds_read_b128 v[158:161], v130 offset:3072
	ds_read_b128 v[130:133], v142
	ds_read_b128 v[134:137], v142 offset:1024
	ds_read_b128 v[138:141], v142 offset:2048
	ds_read_b128 v[142:145], v142 offset:3072
	v_lshl_add_u64 v[246:247], v[234:235], 0, s[80:81]
	s_add_i32 m0, s8, 0xc000
	s_waitcnt lgkmcnt(0)
	ds_read_b128 v[174:177], v244
	ds_read_b128 v[190:193], v244 offset:1024
	ds_read_b128 v[170:173], v244 offset:2048
	ds_read_b128 v[186:189], v244 offset:3072
	ds_read_b128 v[166:169], v244 offset:4096
	ds_read_b128 v[182:185], v244 offset:5120
	ds_read_b128 v[162:165], v244 offset:6144
	ds_read_b128 v[178:181], v244 offset:7168
	global_load_lds_dwordx4 v[246:247], off
	v_lshl_add_u64 v[246:247], v[236:237], 0, s[80:81]
	s_add_i32 m0, s8, 0xe000
	s_nop 0
	global_load_lds_dwordx4 v[246:247], off
	s_waitcnt vmcnt(8)
	s_waitcnt lgkmcnt(0)
	s_barrier
	s_setprio 0
	s_waitcnt lgkmcnt(0)
	v_mfma_f32_16x16x32_bf16 v[118:121], v[146:149], v[174:177], v[118:121]
	v_mfma_f32_16x16x32_bf16 v[126:129], v[154:157], v[174:177], v[126:129]
	v_mfma_f32_16x16x32_bf16 v[102:105], v[146:149], v[170:173], v[102:105]
	v_mfma_f32_16x16x32_bf16 v[110:113], v[154:157], v[170:173], v[110:113]
	v_mfma_f32_16x16x32_bf16 v[86:89], v[146:149], v[166:169], v[86:89]
	v_mfma_f32_16x16x32_bf16 v[94:97], v[154:157], v[166:169], v[94:97]
	v_mfma_f32_16x16x32_bf16 v[70:73], v[146:149], v[162:165], v[70:73]
	v_mfma_f32_16x16x32_bf16 v[78:81], v[154:157], v[162:165], v[78:81]
	v_mfma_f32_16x16x32_bf16 v[118:121], v[150:153], v[190:193], v[118:121]
	v_mfma_f32_16x16x32_bf16 v[126:129], v[158:161], v[190:193], v[126:129]
	v_mfma_f32_16x16x32_bf16 v[102:105], v[150:153], v[186:189], v[102:105]
	v_mfma_f32_16x16x32_bf16 v[110:113], v[158:161], v[186:189], v[110:113]
	v_mfma_f32_16x16x32_bf16 v[86:89], v[150:153], v[182:185], v[86:89]
	v_mfma_f32_16x16x32_bf16 v[94:97], v[158:161], v[182:185], v[94:97]
	v_mfma_f32_16x16x32_bf16 v[70:73], v[150:153], v[178:181], v[70:73]
	v_mfma_f32_16x16x32_bf16 v[78:81], v[158:161], v[178:181], v[78:81]
	s_setprio 1
	s_setprio 0
	v_mfma_f32_16x16x32_bf16 v[122:125], v[130:133], v[174:177], v[122:125]
	v_mfma_f32_16x16x32_bf16 v[114:117], v[138:141], v[174:177], v[114:117]
	v_mfma_f32_16x16x32_bf16 v[106:109], v[130:133], v[170:173], v[106:109]
	v_mfma_f32_16x16x32_bf16 v[98:101], v[138:141], v[170:173], v[98:101]
	v_mfma_f32_16x16x32_bf16 v[90:93], v[130:133], v[166:169], v[90:93]
	v_mfma_f32_16x16x32_bf16 v[82:85], v[138:141], v[166:169], v[82:85]
	v_mfma_f32_16x16x32_bf16 v[74:77], v[130:133], v[162:165], v[74:77]
	v_mfma_f32_16x16x32_bf16 v[66:69], v[138:141], v[162:165], v[66:69]
	v_mfma_f32_16x16x32_bf16 v[122:125], v[134:137], v[190:193], v[122:125]
	v_mfma_f32_16x16x32_bf16 v[114:117], v[142:145], v[190:193], v[114:117]
	v_mfma_f32_16x16x32_bf16 v[106:109], v[134:137], v[186:189], v[106:109]
	v_mfma_f32_16x16x32_bf16 v[98:101], v[142:145], v[186:189], v[98:101]
	v_mfma_f32_16x16x32_bf16 v[90:93], v[134:137], v[182:185], v[90:93]
	v_mfma_f32_16x16x32_bf16 v[82:85], v[142:145], v[182:185], v[82:85]
	v_mfma_f32_16x16x32_bf16 v[74:77], v[134:137], v[178:181], v[74:77]
	v_mfma_f32_16x16x32_bf16 v[66:69], v[142:145], v[178:181], v[66:69]
	s_setprio 1
	s_barrier
	v_cndmask_b32_e64 v246, 0, 1, s[50:51]
	v_cmp_ne_u32_e64 s[48:49], 1, v246
	s_andn2_b64 vcc, exec, s[50:51]
	s_cbranch_vccnz .LBB0_178
	ds_read_b128 v[174:177], v244 offset:16384
	ds_read_b128 v[190:193], v244 offset:17408
	ds_read_b128 v[170:173], v244 offset:18432
	ds_read_b128 v[186:189], v244 offset:19456
	ds_read_b128 v[166:169], v244 offset:20480
	ds_read_b128 v[182:185], v244 offset:21504
	ds_read_b128 v[162:165], v244 offset:22528
	ds_read_b128 v[178:181], v244 offset:23552
.LBB0_178:
	s_add_u32 s82, s0, s80
	s_addc_u32 s83, s1, s81
	s_add_u32 s84, s82, 0x460000
	s_addc_u32 s85, s83, 0
	s_cmp_eq_u32 s80, 0x41a0000
	s_cselect_b64 s[86:87], -1, 0
	s_and_b64 s[82:83], s[86:87], exec
	s_cselect_b32 s83, s71, s97
	s_cselect_b32 s82, s73, s79
	s_mov_b32 m0, s9
	s_cselect_b32 s85, s22, s85
	s_cselect_b32 s84, s69, s84
	s_add_u32 vcc_lo, s82, 0x4000
	global_load_lds_dwordx4 v194, s[82:83]
	s_mov_b32 m0, s10
	s_addc_u32 vcc_hi, s83, 0
	global_load_lds_dwordx4 v196, s[82:83]
	s_mov_b32 m0, s11
	s_nop 0
	global_load_lds_dwordx4 v194, vcc
	v_lshl_add_u64 v[246:247], vcc, 0, v[196:197]
	s_mov_b32 m0, s12
	s_and_b64 vcc, exec, s[48:49]
	global_load_lds_dwordx4 v[246:247], off
	s_mov_b64 s[98:99], s[84:85]
	s_waitcnt vmcnt(6)
	s_waitcnt lgkmcnt(0)
	s_barrier
	s_cbranch_vccnz .LBB0_180
	s_setprio 0
	s_waitcnt lgkmcnt(0)
	v_mfma_f32_16x16x32_bf16 v[54:57], v[146:149], v[174:177], v[54:57]
	v_mfma_f32_16x16x32_bf16 v[62:65], v[154:157], v[174:177], v[62:65]
	v_mfma_f32_16x16x32_bf16 v[38:41], v[146:149], v[170:173], v[38:41]
	v_mfma_f32_16x16x32_bf16 v[46:49], v[154:157], v[170:173], v[46:49]
	v_mfma_f32_16x16x32_bf16 v[22:25], v[146:149], v[166:169], v[22:25]
	v_mfma_f32_16x16x32_bf16 v[30:33], v[154:157], v[166:169], v[30:33]
	v_mfma_f32_16x16x32_bf16 v[10:13], v[146:149], v[162:165], v[10:13]
	v_mfma_f32_16x16x32_bf16 v[14:17], v[154:157], v[162:165], v[14:17]
	v_mfma_f32_16x16x32_bf16 v[54:57], v[150:153], v[190:193], v[54:57]
	v_mfma_f32_16x16x32_bf16 v[62:65], v[158:161], v[190:193], v[62:65]
	v_mfma_f32_16x16x32_bf16 v[38:41], v[150:153], v[186:189], v[38:41]
	v_mfma_f32_16x16x32_bf16 v[46:49], v[158:161], v[186:189], v[46:49]
	v_mfma_f32_16x16x32_bf16 v[22:25], v[150:153], v[182:185], v[22:25]
	v_mfma_f32_16x16x32_bf16 v[30:33], v[158:161], v[182:185], v[30:33]
	v_mfma_f32_16x16x32_bf16 v[10:13], v[150:153], v[178:181], v[10:13]
	v_mfma_f32_16x16x32_bf16 v[14:17], v[158:161], v[178:181], v[14:17]
	s_setprio 1
	s_setprio 0
	v_mfma_f32_16x16x32_bf16 v[58:61], v[130:133], v[174:177], v[58:61]
	v_mfma_f32_16x16x32_bf16 v[50:53], v[138:141], v[174:177], v[50:53]
	v_mfma_f32_16x16x32_bf16 v[42:45], v[130:133], v[170:173], v[42:45]
	v_mfma_f32_16x16x32_bf16 v[34:37], v[138:141], v[170:173], v[34:37]
	v_mfma_f32_16x16x32_bf16 v[26:29], v[130:133], v[166:169], v[26:29]
	v_mfma_f32_16x16x32_bf16 v[18:21], v[138:141], v[166:169], v[18:21]
	v_mfma_f32_16x16x32_bf16 v[6:9], v[130:133], v[162:165], v[6:9]
	v_mfma_f32_16x16x32_bf16 v[2:5], v[138:141], v[162:165], v[2:5]
	v_mfma_f32_16x16x32_bf16 v[58:61], v[134:137], v[190:193], v[58:61]
	v_mfma_f32_16x16x32_bf16 v[50:53], v[142:145], v[190:193], v[50:53]
	v_mfma_f32_16x16x32_bf16 v[42:45], v[134:137], v[186:189], v[42:45]
	v_mfma_f32_16x16x32_bf16 v[34:37], v[142:145], v[186:189], v[34:37]
	v_mfma_f32_16x16x32_bf16 v[26:29], v[134:137], v[182:185], v[26:29]
	v_mfma_f32_16x16x32_bf16 v[18:21], v[142:145], v[182:185], v[18:21]
	v_mfma_f32_16x16x32_bf16 v[6:9], v[134:137], v[178:181], v[6:9]
	v_mfma_f32_16x16x32_bf16 v[2:5], v[142:145], v[178:181], v[2:5]
	s_setprio 1
.LBB0_180:
	s_and_b64 vcc, s[46:47], s[86:87]
	v_cndmask_b32_e64 v131, v233, 0, vcc
	v_cndmask_b32_e32 v130, v232, v198, vcc
	v_lshl_add_u64 v[246:247], s[84:85], 0, v[130:131]
	s_barrier
	s_mov_b32 m0, s8
	s_nop 0
	global_load_lds_dwordx4 v194, s[98:99]
	s_mov_b32 m0, s13
	s_nop 0
	global_load_lds_dwordx4 v196, s[98:99]
	v_add_u32_e32 v130, 0x18000, v243
	v_add_u32_e32 v142, 0x1c000, v243
	ds_read_b128 v[146:149], v130
	ds_read_b128 v[150:153], v130 offset:1024
	ds_read_b128 v[154:157], v130 offset:2048
	ds_read_b128 v[158:161], v130 offset:3072
	ds_read_b128 v[130:133], v142
	ds_read_b128 v[134:137], v142 offset:1024
	ds_read_b128 v[138:141], v142 offset:2048
	ds_read_b128 v[142:145], v142 offset:3072
	s_mov_b32 m0, s14
	v_lshl_add_u64 v[248:249], v[246:247], 0, v[194:195]
	s_waitcnt lgkmcnt(0)
	ds_read_b128 v[174:177], v244 offset:32768
	ds_read_b128 v[190:193], v244 offset:33792
	ds_read_b128 v[170:173], v244 offset:34816
	ds_read_b128 v[186:189], v244 offset:35840
	ds_read_b128 v[166:169], v244 offset:36864
	ds_read_b128 v[182:185], v244 offset:37888
	ds_read_b128 v[162:165], v244 offset:38912
	ds_read_b128 v[178:181], v244 offset:39936
	global_load_lds_dwordx4 v[248:249], off
	v_lshl_add_u64 v[246:247], v[246:247], 0, v[196:197]
	s_mov_b32 m0, s15
	s_nop 0
	global_load_lds_dwordx4 v[246:247], off
	s_waitcnt vmcnt(8)
	s_waitcnt lgkmcnt(0)
	s_barrier
	s_setprio 0
	s_waitcnt lgkmcnt(0)
	v_mfma_f32_16x16x32_bf16 v[118:121], v[146:149], v[174:177], v[118:121]
	v_mfma_f32_16x16x32_bf16 v[126:129], v[154:157], v[174:177], v[126:129]
	v_mfma_f32_16x16x32_bf16 v[102:105], v[146:149], v[170:173], v[102:105]
	v_mfma_f32_16x16x32_bf16 v[110:113], v[154:157], v[170:173], v[110:113]
	v_mfma_f32_16x16x32_bf16 v[86:89], v[146:149], v[166:169], v[86:89]
	v_mfma_f32_16x16x32_bf16 v[94:97], v[154:157], v[166:169], v[94:97]
	v_mfma_f32_16x16x32_bf16 v[70:73], v[146:149], v[162:165], v[70:73]
	v_mfma_f32_16x16x32_bf16 v[78:81], v[154:157], v[162:165], v[78:81]
	v_mfma_f32_16x16x32_bf16 v[118:121], v[150:153], v[190:193], v[118:121]
	v_mfma_f32_16x16x32_bf16 v[126:129], v[158:161], v[190:193], v[126:129]
	v_mfma_f32_16x16x32_bf16 v[102:105], v[150:153], v[186:189], v[102:105]
	v_mfma_f32_16x16x32_bf16 v[110:113], v[158:161], v[186:189], v[110:113]
	v_mfma_f32_16x16x32_bf16 v[86:89], v[150:153], v[182:185], v[86:89]
	v_mfma_f32_16x16x32_bf16 v[94:97], v[158:161], v[182:185], v[94:97]
	v_mfma_f32_16x16x32_bf16 v[70:73], v[150:153], v[178:181], v[70:73]
	v_mfma_f32_16x16x32_bf16 v[78:81], v[158:161], v[178:181], v[78:81]
	s_setprio 1
	s_setprio 0
	v_mfma_f32_16x16x32_bf16 v[122:125], v[130:133], v[174:177], v[122:125]
	v_mfma_f32_16x16x32_bf16 v[114:117], v[138:141], v[174:177], v[114:117]
	v_mfma_f32_16x16x32_bf16 v[106:109], v[130:133], v[170:173], v[106:109]
	v_mfma_f32_16x16x32_bf16 v[98:101], v[138:141], v[170:173], v[98:101]
	v_mfma_f32_16x16x32_bf16 v[90:93], v[130:133], v[166:169], v[90:93]
	v_mfma_f32_16x16x32_bf16 v[82:85], v[138:141], v[166:169], v[82:85]
	v_mfma_f32_16x16x32_bf16 v[74:77], v[130:133], v[162:165], v[74:77]
	v_mfma_f32_16x16x32_bf16 v[66:69], v[138:141], v[162:165], v[66:69]
	v_mfma_f32_16x16x32_bf16 v[122:125], v[134:137], v[190:193], v[122:125]
	v_mfma_f32_16x16x32_bf16 v[114:117], v[142:145], v[190:193], v[114:117]
	v_mfma_f32_16x16x32_bf16 v[106:109], v[134:137], v[186:189], v[106:109]
	v_mfma_f32_16x16x32_bf16 v[98:101], v[142:145], v[186:189], v[98:101]
	v_mfma_f32_16x16x32_bf16 v[90:93], v[134:137], v[182:185], v[90:93]
	v_mfma_f32_16x16x32_bf16 v[82:85], v[142:145], v[182:185], v[82:85]
	v_mfma_f32_16x16x32_bf16 v[74:77], v[134:137], v[178:181], v[74:77]
	v_mfma_f32_16x16x32_bf16 v[66:69], v[142:145], v[178:181], v[66:69]
	s_setprio 1
	s_barrier
	s_and_b64 vcc, exec, s[48:49]
	s_cbranch_vccnz .LBB0_182
	ds_read_b128 v[174:177], v244 offset:49152
	ds_read_b128 v[190:193], v244 offset:50176
	ds_read_b128 v[170:173], v244 offset:51200
	ds_read_b128 v[186:189], v244 offset:52224
	ds_read_b128 v[166:169], v244 offset:53248
	ds_read_b128 v[182:185], v244 offset:54272
	ds_read_b128 v[162:165], v244 offset:55296
	ds_read_b128 v[178:181], v244 offset:56320
.LBB0_182:
	s_add_u32 s86, s82, 0x120000
	s_addc_u32 s87, s83, 0
	s_add_u32 s84, s84, 0x230000
	s_addc_u32 s85, s85, 0
	s_mov_b32 m0, s17
	s_add_u32 s82, s82, 0x124000
	global_load_lds_dwordx4 v194, s[86:87]
	s_mov_b32 m0, s54
	s_addc_u32 s83, s83, 0
	global_load_lds_dwordx4 v196, s[86:87]
	s_mov_b32 m0, s89
	s_and_b64 vcc, exec, s[48:49]
	global_load_lds_dwordx4 v194, s[82:83]
	s_mov_b32 m0, s90
	s_nop 0
	global_load_lds_dwordx4 v196, s[82:83]
	s_mov_b64 s[100:101], s[84:85]
	s_waitcnt vmcnt(6)
	s_waitcnt lgkmcnt(0)
	s_barrier
	s_cbranch_vccnz .LBB0_175
	s_setprio 0
	s_waitcnt lgkmcnt(0)
	v_mfma_f32_16x16x32_bf16 v[54:57], v[146:149], v[174:177], v[54:57]
	v_mfma_f32_16x16x32_bf16 v[62:65], v[154:157], v[174:177], v[62:65]
	v_mfma_f32_16x16x32_bf16 v[38:41], v[146:149], v[170:173], v[38:41]
	v_mfma_f32_16x16x32_bf16 v[46:49], v[154:157], v[170:173], v[46:49]
	v_mfma_f32_16x16x32_bf16 v[22:25], v[146:149], v[166:169], v[22:25]
	v_mfma_f32_16x16x32_bf16 v[30:33], v[154:157], v[166:169], v[30:33]
	v_mfma_f32_16x16x32_bf16 v[10:13], v[146:149], v[162:165], v[10:13]
	v_mfma_f32_16x16x32_bf16 v[14:17], v[154:157], v[162:165], v[14:17]
	v_mfma_f32_16x16x32_bf16 v[54:57], v[150:153], v[190:193], v[54:57]
	v_mfma_f32_16x16x32_bf16 v[62:65], v[158:161], v[190:193], v[62:65]
	v_mfma_f32_16x16x32_bf16 v[38:41], v[150:153], v[186:189], v[38:41]
	v_mfma_f32_16x16x32_bf16 v[46:49], v[158:161], v[186:189], v[46:49]
	v_mfma_f32_16x16x32_bf16 v[22:25], v[150:153], v[182:185], v[22:25]
	v_mfma_f32_16x16x32_bf16 v[30:33], v[158:161], v[182:185], v[30:33]
	v_mfma_f32_16x16x32_bf16 v[10:13], v[150:153], v[178:181], v[10:13]
	v_mfma_f32_16x16x32_bf16 v[14:17], v[158:161], v[178:181], v[14:17]
	s_setprio 1
	s_setprio 0
	v_mfma_f32_16x16x32_bf16 v[58:61], v[130:133], v[174:177], v[58:61]
	v_mfma_f32_16x16x32_bf16 v[50:53], v[138:141], v[174:177], v[50:53]
	v_mfma_f32_16x16x32_bf16 v[42:45], v[130:133], v[170:173], v[42:45]
	v_mfma_f32_16x16x32_bf16 v[34:37], v[138:141], v[170:173], v[34:37]
	v_mfma_f32_16x16x32_bf16 v[26:29], v[130:133], v[166:169], v[26:29]
	v_mfma_f32_16x16x32_bf16 v[18:21], v[138:141], v[166:169], v[18:21]
	v_mfma_f32_16x16x32_bf16 v[6:9], v[130:133], v[162:165], v[6:9]
	v_mfma_f32_16x16x32_bf16 v[2:5], v[138:141], v[162:165], v[2:5]
	v_mfma_f32_16x16x32_bf16 v[58:61], v[134:137], v[190:193], v[58:61]
	v_mfma_f32_16x16x32_bf16 v[50:53], v[142:145], v[190:193], v[50:53]
	v_mfma_f32_16x16x32_bf16 v[42:45], v[134:137], v[186:189], v[42:45]
	v_mfma_f32_16x16x32_bf16 v[34:37], v[142:145], v[186:189], v[34:37]
	v_mfma_f32_16x16x32_bf16 v[26:29], v[134:137], v[182:185], v[26:29]
	v_mfma_f32_16x16x32_bf16 v[18:21], v[142:145], v[182:185], v[18:21]
	v_mfma_f32_16x16x32_bf16 v[6:9], v[134:137], v[178:181], v[6:9]
	v_mfma_f32_16x16x32_bf16 v[2:5], v[142:145], v[178:181], v[2:5]
	s_setprio 1
	s_branch .LBB0_175

.LBB0_559:
	s_mov_b32 m0, s55
	s_nop 0
	global_load_lds_dwordx4 v194, s[100:101]
	s_mov_b32 m0, s67
	s_nop 0
	global_load_lds_dwordx4 v196, s[100:101]
	ds_read_b128 v[146:149], v227
	ds_read_b128 v[150:153], v227 offset:1024
	ds_read_b128 v[154:157], v227 offset:2048
	ds_read_b128 v[158:161], v227 offset:3072
	ds_read_b128 v[130:133], v228
	ds_read_b128 v[134:137], v228 offset:1024
	ds_read_b128 v[138:141], v228 offset:2048
	ds_read_b128 v[142:145], v228 offset:3072
	v_lshl_add_u64 v[234:235], v[216:217], 0, s[58:59]
	s_add_i32 m0, s8, 0xc000
	s_waitcnt lgkmcnt(0)
	ds_read_b128 v[174:177], v229
	ds_read_b128 v[190:193], v229 offset:1024
	ds_read_b128 v[170:173], v229 offset:2048
	ds_read_b128 v[186:189], v229 offset:3072
	ds_read_b128 v[166:169], v229 offset:4096
	ds_read_b128 v[182:185], v229 offset:5120
	ds_read_b128 v[162:165], v229 offset:6144
	ds_read_b128 v[178:181], v229 offset:7168
	global_load_lds_dwordx4 v[234:235], off
	v_lshl_add_u64 v[234:235], v[218:219], 0, s[58:59]
	s_add_i32 m0, s8, 0xe000
	s_nop 0
	global_load_lds_dwordx4 v[234:235], off
	s_waitcnt vmcnt(8)
	s_waitcnt lgkmcnt(0)
	s_barrier
	s_setprio 0
	s_waitcnt lgkmcnt(0)
	v_mfma_f32_16x16x32_bf16 v[126:129], v[146:149], v[174:177], v[126:129]
	v_mfma_f32_16x16x32_bf16 v[122:125], v[154:157], v[174:177], v[122:125]
	v_mfma_f32_16x16x32_bf16 v[110:113], v[146:149], v[170:173], v[110:113]
	v_mfma_f32_16x16x32_bf16 v[106:109], v[154:157], v[170:173], v[106:109]
	v_mfma_f32_16x16x32_bf16 v[94:97], v[146:149], v[166:169], v[94:97]
	v_mfma_f32_16x16x32_bf16 v[90:93], v[154:157], v[166:169], v[90:93]
	v_mfma_f32_16x16x32_bf16 v[78:81], v[146:149], v[162:165], v[78:81]
	v_mfma_f32_16x16x32_bf16 v[74:77], v[154:157], v[162:165], v[74:77]
	v_mfma_f32_16x16x32_bf16 v[126:129], v[150:153], v[190:193], v[126:129]
	v_mfma_f32_16x16x32_bf16 v[122:125], v[158:161], v[190:193], v[122:125]
	v_mfma_f32_16x16x32_bf16 v[110:113], v[150:153], v[186:189], v[110:113]
	v_mfma_f32_16x16x32_bf16 v[106:109], v[158:161], v[186:189], v[106:109]
	v_mfma_f32_16x16x32_bf16 v[94:97], v[150:153], v[182:185], v[94:97]
	v_mfma_f32_16x16x32_bf16 v[90:93], v[158:161], v[182:185], v[90:93]
	v_mfma_f32_16x16x32_bf16 v[78:81], v[150:153], v[178:181], v[78:81]
	v_mfma_f32_16x16x32_bf16 v[74:77], v[158:161], v[178:181], v[74:77]
	s_setprio 1
	s_setprio 0
	v_mfma_f32_16x16x32_bf16 v[118:121], v[130:133], v[174:177], v[118:121]
	v_mfma_f32_16x16x32_bf16 v[114:117], v[138:141], v[174:177], v[114:117]
	v_mfma_f32_16x16x32_bf16 v[102:105], v[130:133], v[170:173], v[102:105]
	v_mfma_f32_16x16x32_bf16 v[98:101], v[138:141], v[170:173], v[98:101]
	v_mfma_f32_16x16x32_bf16 v[86:89], v[130:133], v[166:169], v[86:89]
	v_mfma_f32_16x16x32_bf16 v[82:85], v[138:141], v[166:169], v[82:85]
	v_mfma_f32_16x16x32_bf16 v[70:73], v[130:133], v[162:165], v[70:73]
	v_mfma_f32_16x16x32_bf16 v[66:69], v[138:141], v[162:165], v[66:69]
	v_mfma_f32_16x16x32_bf16 v[118:121], v[134:137], v[190:193], v[118:121]
	v_mfma_f32_16x16x32_bf16 v[114:117], v[142:145], v[190:193], v[114:117]
	v_mfma_f32_16x16x32_bf16 v[102:105], v[134:137], v[186:189], v[102:105]
	v_mfma_f32_16x16x32_bf16 v[98:101], v[142:145], v[186:189], v[98:101]
	v_mfma_f32_16x16x32_bf16 v[86:89], v[134:137], v[182:185], v[86:89]
	v_mfma_f32_16x16x32_bf16 v[82:85], v[142:145], v[182:185], v[82:85]
	v_mfma_f32_16x16x32_bf16 v[70:73], v[134:137], v[178:181], v[70:73]
	v_mfma_f32_16x16x32_bf16 v[66:69], v[142:145], v[178:181], v[66:69]
	s_setprio 1
	s_barrier
	v_cmp_ne_u32_e64 s[42:43], 1, v233
	s_andn2_b64 vcc, exec, s[44:45]
	s_cbranch_vccnz .LBB0_561
	ds_read_b128 v[174:177], v229 offset:16384
	ds_read_b128 v[190:193], v229 offset:17408
	ds_read_b128 v[170:173], v229 offset:18432
	ds_read_b128 v[186:189], v229 offset:19456
	ds_read_b128 v[166:169], v229 offset:20480
	ds_read_b128 v[182:185], v229 offset:21504
	ds_read_b128 v[162:165], v229 offset:22528
	ds_read_b128 v[178:181], v229 offset:23552
.LBB0_561:
	s_add_u32 s60, s56, s58
	s_addc_u32 s61, s57, s59
	s_add_u32 s62, s60, 0x440000
	s_addc_u32 s63, s61, 0
	s_cmp_eq_u32 s58, 0x3fc0000
	s_cselect_b64 s[68:69], -1, 0
	s_and_b64 s[60:61], s[68:69], exec
	s_cselect_b32 s61, s37, s72
	s_cselect_b32 s60, s47, s53
	s_mov_b32 m0, s9
	s_cselect_b32 s63, s1, s63
	s_cselect_b32 s62, s24, s62
	s_add_u32 s74, s60, 0x4000
	global_load_lds_dwordx4 v194, s[60:61]
	s_mov_b32 m0, s10
	s_addc_u32 s75, s61, 0
	global_load_lds_dwordx4 v196, s[60:61]
	s_mov_b32 m0, s11
	s_and_b64 vcc, exec, s[42:43]
	global_load_lds_dwordx4 v194, s[74:75]
	s_mov_b32 m0, s12
	s_nop 0
	global_load_lds_dwordx4 v196, s[74:75]
	s_mov_b64 s[98:99], s[62:63]
	s_waitcnt vmcnt(6)
	s_waitcnt lgkmcnt(0)
	s_barrier
	s_cbranch_vccnz .LBB0_563
	s_setprio 0
	s_waitcnt lgkmcnt(0)
	v_mfma_f32_16x16x32_bf16 v[62:65], v[146:149], v[174:177], v[62:65]
	v_mfma_f32_16x16x32_bf16 v[58:61], v[154:157], v[174:177], v[58:61]
	v_mfma_f32_16x16x32_bf16 v[46:49], v[146:149], v[170:173], v[46:49]
	v_mfma_f32_16x16x32_bf16 v[42:45], v[154:157], v[170:173], v[42:45]
	v_mfma_f32_16x16x32_bf16 v[30:33], v[146:149], v[166:169], v[30:33]
	v_mfma_f32_16x16x32_bf16 v[26:29], v[154:157], v[166:169], v[26:29]
	v_mfma_f32_16x16x32_bf16 v[14:17], v[146:149], v[162:165], v[14:17]
	v_mfma_f32_16x16x32_bf16 v[10:13], v[154:157], v[162:165], v[10:13]
	v_mfma_f32_16x16x32_bf16 v[62:65], v[150:153], v[190:193], v[62:65]
	v_mfma_f32_16x16x32_bf16 v[58:61], v[158:161], v[190:193], v[58:61]
	v_mfma_f32_16x16x32_bf16 v[46:49], v[150:153], v[186:189], v[46:49]
	v_mfma_f32_16x16x32_bf16 v[42:45], v[158:161], v[186:189], v[42:45]
	v_mfma_f32_16x16x32_bf16 v[30:33], v[150:153], v[182:185], v[30:33]
	v_mfma_f32_16x16x32_bf16 v[26:29], v[158:161], v[182:185], v[26:29]
	v_mfma_f32_16x16x32_bf16 v[14:17], v[150:153], v[178:181], v[14:17]
	v_mfma_f32_16x16x32_bf16 v[10:13], v[158:161], v[178:181], v[10:13]
	s_setprio 1
	s_setprio 0
	v_mfma_f32_16x16x32_bf16 v[54:57], v[130:133], v[174:177], v[54:57]
	v_mfma_f32_16x16x32_bf16 v[50:53], v[138:141], v[174:177], v[50:53]
	v_mfma_f32_16x16x32_bf16 v[38:41], v[130:133], v[170:173], v[38:41]
	v_mfma_f32_16x16x32_bf16 v[34:37], v[138:141], v[170:173], v[34:37]
	v_mfma_f32_16x16x32_bf16 v[22:25], v[130:133], v[166:169], v[22:25]
	v_mfma_f32_16x16x32_bf16 v[18:21], v[138:141], v[166:169], v[18:21]
	v_mfma_f32_16x16x32_bf16 v[6:9], v[130:133], v[162:165], v[6:9]
	v_mfma_f32_16x16x32_bf16 v[2:5], v[138:141], v[162:165], v[2:5]
	v_mfma_f32_16x16x32_bf16 v[54:57], v[134:137], v[190:193], v[54:57]
	v_mfma_f32_16x16x32_bf16 v[50:53], v[142:145], v[190:193], v[50:53]
	v_mfma_f32_16x16x32_bf16 v[38:41], v[134:137], v[186:189], v[38:41]
	v_mfma_f32_16x16x32_bf16 v[34:37], v[142:145], v[186:189], v[34:37]
	v_mfma_f32_16x16x32_bf16 v[22:25], v[134:137], v[182:185], v[22:25]
	v_mfma_f32_16x16x32_bf16 v[18:21], v[142:145], v[182:185], v[18:21]
	v_mfma_f32_16x16x32_bf16 v[6:9], v[134:137], v[178:181], v[6:9]
	v_mfma_f32_16x16x32_bf16 v[2:5], v[142:145], v[178:181], v[2:5]
	s_setprio 1
.LBB0_563:
	s_and_b64 vcc, s[40:41], s[68:69]
	v_cndmask_b32_e64 v131, v215, 0, vcc
	v_cndmask_b32_e32 v130, v214, v198, vcc
	v_lshl_add_u64 v[234:235], s[62:63], 0, v[130:131]
	s_barrier
	s_mov_b32 m0, s8
	s_nop 0
	global_load_lds_dwordx4 v194, s[98:99]
	s_mov_b32 m0, s13
	s_nop 0
	global_load_lds_dwordx4 v196, s[98:99]
	v_add_u32_e32 v130, 0x18000, v226
	v_add_u32_e32 v142, 0x1c000, v226
	ds_read_b128 v[146:149], v130
	ds_read_b128 v[150:153], v130 offset:1024
	ds_read_b128 v[154:157], v130 offset:2048
	ds_read_b128 v[158:161], v130 offset:3072
	ds_read_b128 v[130:133], v142
	ds_read_b128 v[134:137], v142 offset:1024
	ds_read_b128 v[138:141], v142 offset:2048
	ds_read_b128 v[142:145], v142 offset:3072
	s_mov_b32 m0, s14
	v_lshl_add_u64 v[236:237], v[234:235], 0, v[194:195]
	s_waitcnt lgkmcnt(0)
	ds_read_b128 v[174:177], v229 offset:32768
	ds_read_b128 v[190:193], v229 offset:33792
	ds_read_b128 v[170:173], v229 offset:34816
	ds_read_b128 v[186:189], v229 offset:35840
	ds_read_b128 v[166:169], v229 offset:36864
	ds_read_b128 v[182:185], v229 offset:37888
	ds_read_b128 v[162:165], v229 offset:38912
	ds_read_b128 v[178:181], v229 offset:39936
	global_load_lds_dwordx4 v[236:237], off
	v_lshl_add_u64 v[234:235], v[234:235], 0, v[196:197]
	s_mov_b32 m0, s15
	s_nop 0
	global_load_lds_dwordx4 v[234:235], off
	s_waitcnt vmcnt(8)
	s_waitcnt lgkmcnt(0)
	s_barrier
	s_setprio 0
	s_waitcnt lgkmcnt(0)
	v_mfma_f32_16x16x32_bf16 v[126:129], v[146:149], v[174:177], v[126:129]
	v_mfma_f32_16x16x32_bf16 v[122:125], v[154:157], v[174:177], v[122:125]
	v_mfma_f32_16x16x32_bf16 v[110:113], v[146:149], v[170:173], v[110:113]
	v_mfma_f32_16x16x32_bf16 v[106:109], v[154:157], v[170:173], v[106:109]
	v_mfma_f32_16x16x32_bf16 v[94:97], v[146:149], v[166:169], v[94:97]
	v_mfma_f32_16x16x32_bf16 v[90:93], v[154:157], v[166:169], v[90:93]
	v_mfma_f32_16x16x32_bf16 v[78:81], v[146:149], v[162:165], v[78:81]
	v_mfma_f32_16x16x32_bf16 v[74:77], v[154:157], v[162:165], v[74:77]
	v_mfma_f32_16x16x32_bf16 v[126:129], v[150:153], v[190:193], v[126:129]
	v_mfma_f32_16x16x32_bf16 v[122:125], v[158:161], v[190:193], v[122:125]
	v_mfma_f32_16x16x32_bf16 v[110:113], v[150:153], v[186:189], v[110:113]
	v_mfma_f32_16x16x32_bf16 v[106:109], v[158:161], v[186:189], v[106:109]
	v_mfma_f32_16x16x32_bf16 v[94:97], v[150:153], v[182:185], v[94:97]
	v_mfma_f32_16x16x32_bf16 v[90:93], v[158:161], v[182:185], v[90:93]
	v_mfma_f32_16x16x32_bf16 v[78:81], v[150:153], v[178:181], v[78:81]
	v_mfma_f32_16x16x32_bf16 v[74:77], v[158:161], v[178:181], v[74:77]
	s_setprio 1
	s_setprio 0
	v_mfma_f32_16x16x32_bf16 v[118:121], v[130:133], v[174:177], v[118:121]
	v_mfma_f32_16x16x32_bf16 v[114:117], v[138:141], v[174:177], v[114:117]
	v_mfma_f32_16x16x32_bf16 v[102:105], v[130:133], v[170:173], v[102:105]
	v_mfma_f32_16x16x32_bf16 v[98:101], v[138:141], v[170:173], v[98:101]
	v_mfma_f32_16x16x32_bf16 v[86:89], v[130:133], v[166:169], v[86:89]
	v_mfma_f32_16x16x32_bf16 v[82:85], v[138:141], v[166:169], v[82:85]
	v_mfma_f32_16x16x32_bf16 v[70:73], v[130:133], v[162:165], v[70:73]
	v_mfma_f32_16x16x32_bf16 v[66:69], v[138:141], v[162:165], v[66:69]
	v_mfma_f32_16x16x32_bf16 v[118:121], v[134:137], v[190:193], v[118:121]
	v_mfma_f32_16x16x32_bf16 v[114:117], v[142:145], v[190:193], v[114:117]
	v_mfma_f32_16x16x32_bf16 v[102:105], v[134:137], v[186:189], v[102:105]
	v_mfma_f32_16x16x32_bf16 v[98:101], v[142:145], v[186:189], v[98:101]
	v_mfma_f32_16x16x32_bf16 v[86:89], v[134:137], v[182:185], v[86:89]
	v_mfma_f32_16x16x32_bf16 v[82:85], v[142:145], v[182:185], v[82:85]
	v_mfma_f32_16x16x32_bf16 v[70:73], v[134:137], v[178:181], v[70:73]
	v_mfma_f32_16x16x32_bf16 v[66:69], v[142:145], v[178:181], v[66:69]
	s_setprio 1
	s_barrier
	s_and_b64 vcc, exec, s[42:43]
	s_cbranch_vccnz .LBB0_565
	ds_read_b128 v[174:177], v229 offset:49152
	ds_read_b128 v[190:193], v229 offset:50176
	ds_read_b128 v[170:173], v229 offset:51200
	ds_read_b128 v[186:189], v229 offset:52224
	ds_read_b128 v[166:169], v229 offset:53248
	ds_read_b128 v[182:185], v229 offset:54272
	ds_read_b128 v[162:165], v229 offset:55296
	ds_read_b128 v[178:181], v229 offset:56320
.LBB0_565:
	s_add_u32 s68, s60, 0x40000
	s_addc_u32 s69, s61, 0
	s_add_u32 s62, s62, 0x220000
	s_addc_u32 s63, s63, 0
	s_mov_b32 m0, s17
	s_add_u32 s60, s60, 0x44000
	global_load_lds_dwordx4 v194, s[68:69]
	s_mov_b32 m0, s54
	s_addc_u32 s61, s61, 0
	global_load_lds_dwordx4 v196, s[68:69]
	s_mov_b32 m0, s70
	s_and_b64 vcc, exec, s[42:43]
	global_load_lds_dwordx4 v194, s[60:61]
	s_mov_b32 m0, s71
	s_nop 0
	global_load_lds_dwordx4 v196, s[60:61]
	s_mov_b64 s[100:101], s[62:63]
	s_waitcnt vmcnt(6)
	s_waitcnt lgkmcnt(0)
	s_barrier
	s_cbranch_vccnz .LBB0_558
	s_setprio 0
	s_waitcnt lgkmcnt(0)
	v_mfma_f32_16x16x32_bf16 v[62:65], v[146:149], v[174:177], v[62:65]
	v_mfma_f32_16x16x32_bf16 v[58:61], v[154:157], v[174:177], v[58:61]
	v_mfma_f32_16x16x32_bf16 v[46:49], v[146:149], v[170:173], v[46:49]
	v_mfma_f32_16x16x32_bf16 v[42:45], v[154:157], v[170:173], v[42:45]
	v_mfma_f32_16x16x32_bf16 v[30:33], v[146:149], v[166:169], v[30:33]
	v_mfma_f32_16x16x32_bf16 v[26:29], v[154:157], v[166:169], v[26:29]
	v_mfma_f32_16x16x32_bf16 v[14:17], v[146:149], v[162:165], v[14:17]
	v_mfma_f32_16x16x32_bf16 v[10:13], v[154:157], v[162:165], v[10:13]
	v_mfma_f32_16x16x32_bf16 v[62:65], v[150:153], v[190:193], v[62:65]
	v_mfma_f32_16x16x32_bf16 v[58:61], v[158:161], v[190:193], v[58:61]
	v_mfma_f32_16x16x32_bf16 v[46:49], v[150:153], v[186:189], v[46:49]
	v_mfma_f32_16x16x32_bf16 v[42:45], v[158:161], v[186:189], v[42:45]
	v_mfma_f32_16x16x32_bf16 v[30:33], v[150:153], v[182:185], v[30:33]
	v_mfma_f32_16x16x32_bf16 v[26:29], v[158:161], v[182:185], v[26:29]
	v_mfma_f32_16x16x32_bf16 v[14:17], v[150:153], v[178:181], v[14:17]
	v_mfma_f32_16x16x32_bf16 v[10:13], v[158:161], v[178:181], v[10:13]
	s_setprio 1
	s_setprio 0
	v_mfma_f32_16x16x32_bf16 v[54:57], v[130:133], v[174:177], v[54:57]
	v_mfma_f32_16x16x32_bf16 v[50:53], v[138:141], v[174:177], v[50:53]
	v_mfma_f32_16x16x32_bf16 v[38:41], v[130:133], v[170:173], v[38:41]
	v_mfma_f32_16x16x32_bf16 v[34:37], v[138:141], v[170:173], v[34:37]
	v_mfma_f32_16x16x32_bf16 v[22:25], v[130:133], v[166:169], v[22:25]
	v_mfma_f32_16x16x32_bf16 v[18:21], v[138:141], v[166:169], v[18:21]
	v_mfma_f32_16x16x32_bf16 v[6:9], v[130:133], v[162:165], v[6:9]
	v_mfma_f32_16x16x32_bf16 v[2:5], v[138:141], v[162:165], v[2:5]
	v_mfma_f32_16x16x32_bf16 v[54:57], v[134:137], v[190:193], v[54:57]
	v_mfma_f32_16x16x32_bf16 v[50:53], v[142:145], v[190:193], v[50:53]
	v_mfma_f32_16x16x32_bf16 v[38:41], v[134:137], v[186:189], v[38:41]
	v_mfma_f32_16x16x32_bf16 v[34:37], v[142:145], v[186:189], v[34:37]
	v_mfma_f32_16x16x32_bf16 v[22:25], v[134:137], v[182:185], v[22:25]
	v_mfma_f32_16x16x32_bf16 v[18:21], v[142:145], v[182:185], v[18:21]
	v_mfma_f32_16x16x32_bf16 v[6:9], v[134:137], v[178:181], v[6:9]
	v_mfma_f32_16x16x32_bf16 v[2:5], v[142:145], v[178:181], v[2:5]
	s_setprio 1
	s_branch .LBB0_558

.LBB0_761:
	s_mov_b32 m0, s14
	s_nop 0
	global_load_lds_dwordx4 v194, s[100:101]
	s_mov_b32 m0, s15
	s_nop 0
	global_load_lds_dwordx4 v196, s[100:101]
	ds_read_b128 v[130:133], v237
	ds_read_b128 v[134:137], v237 offset:1024
	ds_read_b128 v[138:141], v237 offset:2048
	ds_read_b128 v[142:145], v237 offset:3072
	ds_read_b128 v[146:149], v238
	ds_read_b128 v[150:153], v238 offset:1024
	ds_read_b128 v[154:157], v238 offset:2048
	ds_read_b128 v[158:161], v238 offset:3072
	s_add_u32 s48, s0, 0x21c000
	s_addc_u32 s49, s1, 0
	s_cmp_eq_u32 s67, 28
	s_cselect_b32 s42, s55, s62
	s_cselect_b32 s43, s29, s63
	s_cselect_b32 s52, s45, s48
	s_cselect_b32 s53, s31, s49
	s_add_u32 s50, s42, 0xe0000
	s_addc_u32 s51, s43, 0
	s_add_u32 s48, s52, 0x220000
	s_addc_u32 s49, s53, 0
	v_lshl_add_u64 v[208:209], s[0:1], 0, v[202:203]
	s_add_i32 m0, s9, 0xc000
	ds_read_b128 v[162:165], v239
	ds_read_b128 v[166:169], v239 offset:1024
	ds_read_b128 v[170:173], v239 offset:2048
	ds_read_b128 v[174:177], v239 offset:3072
	ds_read_b128 v[178:181], v239 offset:4096
	ds_read_b128 v[182:185], v239 offset:5120
	ds_read_b128 v[186:189], v239 offset:6144
	ds_read_b128 v[190:193], v239 offset:7168
	global_load_lds_dwordx4 v[208:209], off
	v_lshl_add_u64 v[208:209], s[0:1], 0, v[200:201]
	s_add_i32 m0, s9, 0xe000
	s_nop 0
	global_load_lds_dwordx4 v[208:209], off
	s_waitcnt vmcnt(8)
	s_waitcnt lgkmcnt(0)
	s_barrier
	s_setprio 0
	s_waitcnt lgkmcnt(0)
	v_mfma_f32_16x16x32_bf16 v[126:129], v[130:133], v[162:165], v[126:129]
	v_mfma_f32_16x16x32_bf16 v[122:125], v[138:141], v[162:165], v[122:125]
	v_mfma_f32_16x16x32_bf16 v[118:121], v[130:133], v[170:173], v[118:121]
	v_mfma_f32_16x16x32_bf16 v[114:117], v[138:141], v[170:173], v[114:117]
	v_mfma_f32_16x16x32_bf16 v[110:113], v[130:133], v[178:181], v[110:113]
	v_mfma_f32_16x16x32_bf16 v[106:109], v[138:141], v[178:181], v[106:109]
	v_mfma_f32_16x16x32_bf16 v[102:105], v[130:133], v[186:189], v[102:105]
	v_mfma_f32_16x16x32_bf16 v[98:101], v[138:141], v[186:189], v[98:101]
	v_mfma_f32_16x16x32_bf16 v[126:129], v[134:137], v[166:169], v[126:129]
	v_mfma_f32_16x16x32_bf16 v[122:125], v[142:145], v[166:169], v[122:125]
	v_mfma_f32_16x16x32_bf16 v[118:121], v[134:137], v[174:177], v[118:121]
	v_mfma_f32_16x16x32_bf16 v[114:117], v[142:145], v[174:177], v[114:117]
	v_mfma_f32_16x16x32_bf16 v[110:113], v[134:137], v[182:185], v[110:113]
	v_mfma_f32_16x16x32_bf16 v[106:109], v[142:145], v[182:185], v[106:109]
	v_mfma_f32_16x16x32_bf16 v[102:105], v[134:137], v[190:193], v[102:105]
	v_mfma_f32_16x16x32_bf16 v[98:101], v[142:145], v[190:193], v[98:101]
	s_setprio 1
	s_setprio 0
	v_mfma_f32_16x16x32_bf16 v[62:65], v[146:149], v[162:165], v[62:65]
	s_add_u32 s60, s52, 0x4000
	s_addc_u32 s61, s53, 0
	v_mfma_f32_16x16x32_bf16 v[58:61], v[154:157], v[162:165], v[58:61]
	v_mfma_f32_16x16x32_bf16 v[54:57], v[146:149], v[170:173], v[54:57]
	v_mfma_f32_16x16x32_bf16 v[50:53], v[154:157], v[170:173], v[50:53]
	v_mfma_f32_16x16x32_bf16 v[46:49], v[146:149], v[178:181], v[46:49]
	v_mfma_f32_16x16x32_bf16 v[42:45], v[154:157], v[178:181], v[42:45]
	v_mfma_f32_16x16x32_bf16 v[38:41], v[146:149], v[186:189], v[38:41]
	v_mfma_f32_16x16x32_bf16 v[34:37], v[154:157], v[186:189], v[34:37]
	v_mfma_f32_16x16x32_bf16 v[62:65], v[150:153], v[166:169], v[62:65]
	v_mfma_f32_16x16x32_bf16 v[58:61], v[158:161], v[166:169], v[58:61]
	v_mfma_f32_16x16x32_bf16 v[54:57], v[150:153], v[174:177], v[54:57]
	v_mfma_f32_16x16x32_bf16 v[50:53], v[158:161], v[174:177], v[50:53]
	v_mfma_f32_16x16x32_bf16 v[46:49], v[150:153], v[182:185], v[46:49]
	v_mfma_f32_16x16x32_bf16 v[42:45], v[158:161], v[182:185], v[42:45]
	v_mfma_f32_16x16x32_bf16 v[38:41], v[150:153], v[190:193], v[38:41]
	v_mfma_f32_16x16x32_bf16 v[34:37], v[158:161], v[190:193], v[34:37]
	s_setprio 1
	s_barrier
	s_add_i32 s68, s16, s8
	s_mov_b32 m0, s68
	ds_read_b128 v[162:165], v239 offset:16384
	ds_read_b128 v[166:169], v239 offset:17408
	ds_read_b128 v[170:173], v239 offset:18432
	ds_read_b128 v[174:177], v239 offset:19456
	ds_read_b128 v[178:181], v239 offset:20480
	ds_read_b128 v[182:185], v239 offset:21504
	ds_read_b128 v[186:189], v239 offset:22528
	ds_read_b128 v[190:193], v239 offset:23552
	global_load_lds_dwordx4 v194, s[42:43]
	s_add_i32 m0, s68, 0x2000
	s_add_u32 s68, s42, 0x4000
	s_addc_u32 s69, s43, 0
	s_add_i32 s70, s17, s8
	global_load_lds_dwordx4 v196, s[42:43]
	s_mov_b32 m0, s70
	s_nop 0
	global_load_lds_dwordx4 v194, s[68:69]
	s_add_i32 m0, s70, 0x2000
	s_nop 0
	global_load_lds_dwordx4 v196, s[68:69]
	s_mov_b64 s[98:99], s[52:53]
	s_waitcnt vmcnt(6)
	s_waitcnt lgkmcnt(0)
	s_barrier
	s_setprio 0
	s_waitcnt lgkmcnt(0)
	v_mfma_f32_16x16x32_bf16 v[94:97], v[130:133], v[162:165], v[94:97]
	v_mfma_f32_16x16x32_bf16 v[90:93], v[138:141], v[162:165], v[90:93]
	v_mfma_f32_16x16x32_bf16 v[86:89], v[130:133], v[170:173], v[86:89]
	v_mfma_f32_16x16x32_bf16 v[82:85], v[138:141], v[170:173], v[82:85]
	v_mfma_f32_16x16x32_bf16 v[78:81], v[130:133], v[178:181], v[78:81]
	v_mfma_f32_16x16x32_bf16 v[74:77], v[138:141], v[178:181], v[74:77]
	v_mfma_f32_16x16x32_bf16 v[70:73], v[130:133], v[186:189], v[70:73]
	v_mfma_f32_16x16x32_bf16 v[66:69], v[138:141], v[186:189], v[66:69]
	v_mfma_f32_16x16x32_bf16 v[94:97], v[134:137], v[166:169], v[94:97]
	v_mfma_f32_16x16x32_bf16 v[90:93], v[142:145], v[166:169], v[90:93]
	v_mfma_f32_16x16x32_bf16 v[86:89], v[134:137], v[174:177], v[86:89]
	v_mfma_f32_16x16x32_bf16 v[82:85], v[142:145], v[174:177], v[82:85]
	v_mfma_f32_16x16x32_bf16 v[78:81], v[134:137], v[182:185], v[78:81]
	v_mfma_f32_16x16x32_bf16 v[74:77], v[142:145], v[182:185], v[74:77]
	v_mfma_f32_16x16x32_bf16 v[70:73], v[134:137], v[190:193], v[70:73]
	v_mfma_f32_16x16x32_bf16 v[66:69], v[142:145], v[190:193], v[66:69]
	s_setprio 1
	s_setprio 0
	v_mfma_f32_16x16x32_bf16 v[30:33], v[146:149], v[162:165], v[30:33]
	v_mfma_f32_16x16x32_bf16 v[26:29], v[154:157], v[162:165], v[26:29]
	v_mfma_f32_16x16x32_bf16 v[22:25], v[146:149], v[170:173], v[22:25]
	v_mfma_f32_16x16x32_bf16 v[18:21], v[154:157], v[170:173], v[18:21]
	v_mfma_f32_16x16x32_bf16 v[14:17], v[146:149], v[178:181], v[14:17]
	v_mfma_f32_16x16x32_bf16 v[10:13], v[154:157], v[178:181], v[10:13]
	v_mfma_f32_16x16x32_bf16 v[6:9], v[146:149], v[186:189], v[6:9]
	v_mfma_f32_16x16x32_bf16 v[2:5], v[154:157], v[186:189], v[2:5]
	v_mfma_f32_16x16x32_bf16 v[30:33], v[150:153], v[166:169], v[30:33]
	v_mfma_f32_16x16x32_bf16 v[26:29], v[158:161], v[166:169], v[26:29]
	v_mfma_f32_16x16x32_bf16 v[22:25], v[150:153], v[174:177], v[22:25]
	v_mfma_f32_16x16x32_bf16 v[18:21], v[158:161], v[174:177], v[18:21]
	v_mfma_f32_16x16x32_bf16 v[14:17], v[150:153], v[182:185], v[14:17]
	v_mfma_f32_16x16x32_bf16 v[10:13], v[158:161], v[182:185], v[10:13]
	v_mfma_f32_16x16x32_bf16 v[6:9], v[150:153], v[190:193], v[6:9]
	v_mfma_f32_16x16x32_bf16 v[2:5], v[158:161], v[190:193], v[2:5]
	s_setprio 1
	s_barrier
	s_mov_b32 m0, s9
	s_nop 0
	global_load_lds_dwordx4 v194, s[98:99]
	s_mov_b32 m0, s10
	s_nop 0
	global_load_lds_dwordx4 v196, s[98:99]
	s_add_i32 s52, 0, 0x18000
	s_add_i32 s53, 0, 0x1c000
	v_add_u32_e32 v142, s52, v228
	v_add_u32_e32 v158, s53, v228
	ds_read_b128 v[130:133], v142
	ds_read_b128 v[134:137], v142 offset:1024
	ds_read_b128 v[138:141], v142 offset:2048
	ds_read_b128 v[142:145], v142 offset:3072
	ds_read_b128 v[146:149], v158
	ds_read_b128 v[150:153], v158 offset:1024
	ds_read_b128 v[154:157], v158 offset:2048
	ds_read_b128 v[158:161], v158 offset:3072
	s_mov_b32 m0, s11
	ds_read_b128 v[162:165], v239 offset:32768
	ds_read_b128 v[166:169], v239 offset:33792
	ds_read_b128 v[170:173], v239 offset:34816
	ds_read_b128 v[174:177], v239 offset:35840
	ds_read_b128 v[178:181], v239 offset:36864
	ds_read_b128 v[182:185], v239 offset:37888
	ds_read_b128 v[186:189], v239 offset:38912
	ds_read_b128 v[190:193], v239 offset:39936
	global_load_lds_dwordx4 v194, s[60:61]
	s_mov_b32 m0, s12
	s_nop 0
	global_load_lds_dwordx4 v196, s[60:61]
	s_waitcnt vmcnt(8)
	s_waitcnt lgkmcnt(0)
	s_barrier
	s_setprio 0
	s_waitcnt lgkmcnt(0)
	v_mfma_f32_16x16x32_bf16 v[126:129], v[130:133], v[162:165], v[126:129]
	v_mfma_f32_16x16x32_bf16 v[122:125], v[138:141], v[162:165], v[122:125]
	v_mfma_f32_16x16x32_bf16 v[118:121], v[130:133], v[170:173], v[118:121]
	v_mfma_f32_16x16x32_bf16 v[114:117], v[138:141], v[170:173], v[114:117]
	v_mfma_f32_16x16x32_bf16 v[110:113], v[130:133], v[178:181], v[110:113]
	v_mfma_f32_16x16x32_bf16 v[106:109], v[138:141], v[178:181], v[106:109]
	v_mfma_f32_16x16x32_bf16 v[102:105], v[130:133], v[186:189], v[102:105]
	v_mfma_f32_16x16x32_bf16 v[98:101], v[138:141], v[186:189], v[98:101]
	v_mfma_f32_16x16x32_bf16 v[126:129], v[134:137], v[166:169], v[126:129]
	v_mfma_f32_16x16x32_bf16 v[122:125], v[142:145], v[166:169], v[122:125]
	v_mfma_f32_16x16x32_bf16 v[118:121], v[134:137], v[174:177], v[118:121]
	v_mfma_f32_16x16x32_bf16 v[114:117], v[142:145], v[174:177], v[114:117]
	v_mfma_f32_16x16x32_bf16 v[110:113], v[134:137], v[182:185], v[110:113]
	v_mfma_f32_16x16x32_bf16 v[106:109], v[142:145], v[182:185], v[106:109]
	v_mfma_f32_16x16x32_bf16 v[102:105], v[134:137], v[190:193], v[102:105]
	v_mfma_f32_16x16x32_bf16 v[98:101], v[142:145], v[190:193], v[98:101]
	s_setprio 1
	s_setprio 0
	v_mfma_f32_16x16x32_bf16 v[62:65], v[146:149], v[162:165], v[62:65]
	v_mfma_f32_16x16x32_bf16 v[58:61], v[154:157], v[162:165], v[58:61]
	v_mfma_f32_16x16x32_bf16 v[54:57], v[146:149], v[170:173], v[54:57]
	v_mfma_f32_16x16x32_bf16 v[50:53], v[154:157], v[170:173], v[50:53]
	v_mfma_f32_16x16x32_bf16 v[46:49], v[146:149], v[178:181], v[46:49]
	v_mfma_f32_16x16x32_bf16 v[42:45], v[154:157], v[178:181], v[42:45]
	v_mfma_f32_16x16x32_bf16 v[38:41], v[146:149], v[186:189], v[38:41]
	v_mfma_f32_16x16x32_bf16 v[34:37], v[154:157], v[186:189], v[34:37]
	v_mfma_f32_16x16x32_bf16 v[62:65], v[150:153], v[166:169], v[62:65]
	v_mfma_f32_16x16x32_bf16 v[58:61], v[158:161], v[166:169], v[58:61]
	v_mfma_f32_16x16x32_bf16 v[54:57], v[150:153], v[174:177], v[54:57]
	v_mfma_f32_16x16x32_bf16 v[50:53], v[158:161], v[174:177], v[50:53]
	v_mfma_f32_16x16x32_bf16 v[46:49], v[150:153], v[182:185], v[46:49]
	v_mfma_f32_16x16x32_bf16 v[42:45], v[158:161], v[182:185], v[42:45]
	v_mfma_f32_16x16x32_bf16 v[38:41], v[150:153], v[190:193], v[38:41]
	v_mfma_f32_16x16x32_bf16 v[34:37], v[158:161], v[190:193], v[34:37]
	s_setprio 1
	s_barrier
	s_add_i32 s52, s52, s8
	s_mov_b32 m0, s52
	ds_read_b128 v[162:165], v239 offset:49152
	ds_read_b128 v[166:169], v239 offset:50176
	ds_read_b128 v[170:173], v239 offset:51200
	ds_read_b128 v[174:177], v239 offset:52224
	ds_read_b128 v[178:181], v239 offset:53248
	ds_read_b128 v[182:185], v239 offset:54272
	ds_read_b128 v[186:189], v239 offset:55296
	ds_read_b128 v[190:193], v239 offset:56320
	global_load_lds_dwordx4 v194, s[50:51]
	s_add_i32 m0, s52, 0x2000
	s_add_u32 s42, s42, 0xe4000
	v_lshl_add_u64 v[208:209], s[50:51], 0, v[196:197]
	s_addc_u32 s43, s43, 0
	s_add_i32 s50, s53, s8
	global_load_lds_dwordx4 v[208:209], off
	s_mov_b32 m0, s50
	s_nop 0
	global_load_lds_dwordx4 v194, s[42:43]
	s_add_i32 m0, s50, 0x2000
	s_nop 0
	global_load_lds_dwordx4 v196, s[42:43]
	s_mov_b64 s[100:101], s[48:49]
	s_waitcnt vmcnt(6)
	s_waitcnt lgkmcnt(0)
	s_barrier
	s_setprio 0
	s_waitcnt lgkmcnt(0)
	v_mfma_f32_16x16x32_bf16 v[94:97], v[130:133], v[162:165], v[94:97]
	v_mfma_f32_16x16x32_bf16 v[90:93], v[138:141], v[162:165], v[90:93]
	v_mfma_f32_16x16x32_bf16 v[86:89], v[130:133], v[170:173], v[86:89]
	v_mfma_f32_16x16x32_bf16 v[82:85], v[138:141], v[170:173], v[82:85]
	v_mfma_f32_16x16x32_bf16 v[78:81], v[130:133], v[178:181], v[78:81]
	v_mfma_f32_16x16x32_bf16 v[74:77], v[138:141], v[178:181], v[74:77]
	v_mfma_f32_16x16x32_bf16 v[70:73], v[130:133], v[186:189], v[70:73]
	v_mfma_f32_16x16x32_bf16 v[66:69], v[138:141], v[186:189], v[66:69]
	v_mfma_f32_16x16x32_bf16 v[94:97], v[134:137], v[166:169], v[94:97]
	v_mfma_f32_16x16x32_bf16 v[90:93], v[142:145], v[166:169], v[90:93]
	v_mfma_f32_16x16x32_bf16 v[86:89], v[134:137], v[174:177], v[86:89]
	v_mfma_f32_16x16x32_bf16 v[82:85], v[142:145], v[174:177], v[82:85]
	v_mfma_f32_16x16x32_bf16 v[78:81], v[134:137], v[182:185], v[78:81]
	v_mfma_f32_16x16x32_bf16 v[74:77], v[142:145], v[182:185], v[74:77]
	v_mfma_f32_16x16x32_bf16 v[70:73], v[134:137], v[190:193], v[70:73]
	v_mfma_f32_16x16x32_bf16 v[66:69], v[142:145], v[190:193], v[66:69]
	s_setprio 1
	s_setprio 0
	v_mfma_f32_16x16x32_bf16 v[30:33], v[146:149], v[162:165], v[30:33]
	v_mfma_f32_16x16x32_bf16 v[26:29], v[154:157], v[162:165], v[26:29]
	v_mfma_f32_16x16x32_bf16 v[22:25], v[146:149], v[170:173], v[22:25]
	v_mfma_f32_16x16x32_bf16 v[18:21], v[154:157], v[170:173], v[18:21]
	v_mfma_f32_16x16x32_bf16 v[14:17], v[146:149], v[178:181], v[14:17]
	v_mfma_f32_16x16x32_bf16 v[10:13], v[154:157], v[178:181], v[10:13]
	v_mfma_f32_16x16x32_bf16 v[6:9], v[146:149], v[186:189], v[6:9]
	v_mfma_f32_16x16x32_bf16 v[2:5], v[154:157], v[186:189], v[2:5]
	v_mfma_f32_16x16x32_bf16 v[30:33], v[150:153], v[166:169], v[30:33]
	v_mfma_f32_16x16x32_bf16 v[26:29], v[158:161], v[166:169], v[26:29]
	v_mfma_f32_16x16x32_bf16 v[22:25], v[150:153], v[174:177], v[22:25]
	v_mfma_f32_16x16x32_bf16 v[18:21], v[158:161], v[174:177], v[18:21]
	v_mfma_f32_16x16x32_bf16 v[14:17], v[150:153], v[182:185], v[14:17]
	v_mfma_f32_16x16x32_bf16 v[10:13], v[158:161], v[182:185], v[10:13]
	v_mfma_f32_16x16x32_bf16 v[6:9], v[150:153], v[190:193], v[6:9]
	v_mfma_f32_16x16x32_bf16 v[2:5], v[158:161], v[190:193], v[2:5]
	s_setprio 1
	s_barrier
	s_add_i32 s67, s67, 2
	s_add_u32 s62, s62, 0x1c0000
	s_addc_u32 s63, s63, 0
	s_add_u32 s0, s0, 0x440000
	s_addc_u32 s1, s1, 0
	s_cmp_gt_u32 s67, 29
	s_cbranch_scc0 .LBB0_761
	s_and_b64 vcc, exec, s[26:27]
	s_cbranch_vccz .LBB0_764
	s_barrier

.LBB0_903:
	s_mov_b32 m0, s23
	s_nop 0
	global_load_lds_dwordx4 v194, s[100:101]
	s_mov_b32 m0, s31
	s_nop 0
	global_load_lds_dwordx4 v196, s[100:101]
	ds_read_b128 v[146:149], v225
	ds_read_b128 v[150:153], v225 offset:1024
	ds_read_b128 v[154:157], v225 offset:2048
	ds_read_b128 v[158:161], v225 offset:3072
	ds_read_b128 v[130:133], v227
	ds_read_b128 v[134:137], v227 offset:1024
	ds_read_b128 v[138:141], v227 offset:2048
	ds_read_b128 v[142:145], v227 offset:3072
	v_lshl_add_u64 v[234:235], v[210:211], 0, s[62:63]
	s_add_i32 m0, s8, 0xc000
	s_waitcnt lgkmcnt(0)
	ds_read_b128 v[174:177], v228
	ds_read_b128 v[190:193], v228 offset:1024
	ds_read_b128 v[170:173], v228 offset:2048
	ds_read_b128 v[186:189], v228 offset:3072
	ds_read_b128 v[166:169], v228 offset:4096
	ds_read_b128 v[182:185], v228 offset:5120
	ds_read_b128 v[162:165], v228 offset:6144
	ds_read_b128 v[178:181], v228 offset:7168
	global_load_lds_dwordx4 v[234:235], off
	v_lshl_add_u64 v[234:235], v[212:213], 0, s[62:63]
	s_add_i32 m0, s8, 0xe000
	s_nop 0
	global_load_lds_dwordx4 v[234:235], off
	s_waitcnt vmcnt(8)
	s_waitcnt lgkmcnt(0)
	s_barrier
	s_setprio 0
	s_waitcnt lgkmcnt(0)
	v_mfma_f32_16x16x32_bf16 v[126:129], v[146:149], v[174:177], v[126:129]
	v_mfma_f32_16x16x32_bf16 v[122:125], v[154:157], v[174:177], v[122:125]
	v_mfma_f32_16x16x32_bf16 v[118:121], v[146:149], v[170:173], v[118:121]
	v_mfma_f32_16x16x32_bf16 v[114:117], v[154:157], v[170:173], v[114:117]
	v_mfma_f32_16x16x32_bf16 v[110:113], v[146:149], v[166:169], v[110:113]
	v_mfma_f32_16x16x32_bf16 v[106:109], v[154:157], v[166:169], v[106:109]
	v_mfma_f32_16x16x32_bf16 v[102:105], v[146:149], v[162:165], v[102:105]
	v_mfma_f32_16x16x32_bf16 v[98:101], v[154:157], v[162:165], v[98:101]
	v_mfma_f32_16x16x32_bf16 v[126:129], v[150:153], v[190:193], v[126:129]
	v_mfma_f32_16x16x32_bf16 v[122:125], v[158:161], v[190:193], v[122:125]
	v_mfma_f32_16x16x32_bf16 v[118:121], v[150:153], v[186:189], v[118:121]
	v_mfma_f32_16x16x32_bf16 v[114:117], v[158:161], v[186:189], v[114:117]
	v_mfma_f32_16x16x32_bf16 v[110:113], v[150:153], v[182:185], v[110:113]
	v_mfma_f32_16x16x32_bf16 v[106:109], v[158:161], v[182:185], v[106:109]
	v_mfma_f32_16x16x32_bf16 v[102:105], v[150:153], v[178:181], v[102:105]
	v_mfma_f32_16x16x32_bf16 v[98:101], v[158:161], v[178:181], v[98:101]
	s_setprio 1
	s_setprio 0
	v_mfma_f32_16x16x32_bf16 v[94:97], v[130:133], v[174:177], v[94:97]
	v_mfma_f32_16x16x32_bf16 v[90:93], v[138:141], v[174:177], v[90:93]
	v_mfma_f32_16x16x32_bf16 v[86:89], v[130:133], v[170:173], v[86:89]
	v_mfma_f32_16x16x32_bf16 v[82:85], v[138:141], v[170:173], v[82:85]
	v_mfma_f32_16x16x32_bf16 v[78:81], v[130:133], v[166:169], v[78:81]
	v_mfma_f32_16x16x32_bf16 v[74:77], v[138:141], v[166:169], v[74:77]
	v_mfma_f32_16x16x32_bf16 v[70:73], v[130:133], v[162:165], v[70:73]
	v_mfma_f32_16x16x32_bf16 v[66:69], v[138:141], v[162:165], v[66:69]
	v_mfma_f32_16x16x32_bf16 v[94:97], v[134:137], v[190:193], v[94:97]
	v_mfma_f32_16x16x32_bf16 v[90:93], v[142:145], v[190:193], v[90:93]
	v_mfma_f32_16x16x32_bf16 v[86:89], v[134:137], v[186:189], v[86:89]
	v_mfma_f32_16x16x32_bf16 v[82:85], v[142:145], v[186:189], v[82:85]
	v_mfma_f32_16x16x32_bf16 v[78:81], v[134:137], v[182:185], v[78:81]
	v_mfma_f32_16x16x32_bf16 v[74:77], v[142:145], v[182:185], v[74:77]
	v_mfma_f32_16x16x32_bf16 v[70:73], v[134:137], v[178:181], v[70:73]
	v_mfma_f32_16x16x32_bf16 v[66:69], v[142:145], v[178:181], v[66:69]
	s_setprio 1
	s_barrier
	v_cmp_ne_u32_e64 s[42:43], 1, v233
	s_andn2_b64 vcc, exec, s[44:45]
	s_cbranch_vccnz .LBB0_905
	ds_read_b128 v[174:177], v228 offset:16384
	ds_read_b128 v[190:193], v228 offset:17408
	ds_read_b128 v[170:173], v228 offset:18432
	ds_read_b128 v[186:189], v228 offset:19456
	ds_read_b128 v[166:169], v228 offset:20480
	ds_read_b128 v[182:185], v228 offset:21504
	ds_read_b128 v[162:165], v228 offset:22528
	ds_read_b128 v[178:181], v228 offset:23552
.LBB0_905:
	s_add_u32 s68, s0, s62
	s_addc_u32 s69, s1, s63
	s_add_u32 s70, s68, 0x440000
	s_addc_u32 s71, s69, 0
	s_cmp_eq_u32 s62, 0x3fc0000
	s_cselect_b64 s[72:73], -1, 0
	s_and_b64 s[68:69], s[72:73], exec
	s_cselect_b32 s69, s37, s77
	s_cselect_b32 s68, s75, s76
	s_mov_b32 m0, s9
	s_cselect_b32 s71, s35, s71
	s_cselect_b32 s70, s74, s70
	s_add_u32 s80, s68, 0x4000
	global_load_lds_dwordx4 v194, s[68:69]
	s_mov_b32 m0, s10
	s_addc_u32 s81, s69, 0
	global_load_lds_dwordx4 v196, s[68:69]
	s_mov_b32 m0, s11
	s_and_b64 vcc, exec, s[42:43]
	global_load_lds_dwordx4 v194, s[80:81]
	s_mov_b32 m0, s12
	s_nop 0
	global_load_lds_dwordx4 v196, s[80:81]
	s_mov_b64 s[98:99], s[70:71]
	s_waitcnt vmcnt(6)
	s_waitcnt lgkmcnt(0)
	s_barrier
	s_cbranch_vccnz .LBB0_907
	s_setprio 0
	s_waitcnt lgkmcnt(0)
	v_mfma_f32_16x16x32_bf16 v[62:65], v[146:149], v[174:177], v[62:65]
	v_mfma_f32_16x16x32_bf16 v[58:61], v[154:157], v[174:177], v[58:61]
	v_mfma_f32_16x16x32_bf16 v[54:57], v[146:149], v[170:173], v[54:57]
	v_mfma_f32_16x16x32_bf16 v[50:53], v[154:157], v[170:173], v[50:53]
	v_mfma_f32_16x16x32_bf16 v[46:49], v[146:149], v[166:169], v[46:49]
	v_mfma_f32_16x16x32_bf16 v[42:45], v[154:157], v[166:169], v[42:45]
	v_mfma_f32_16x16x32_bf16 v[38:41], v[146:149], v[162:165], v[38:41]
	v_mfma_f32_16x16x32_bf16 v[34:37], v[154:157], v[162:165], v[34:37]
	v_mfma_f32_16x16x32_bf16 v[62:65], v[150:153], v[190:193], v[62:65]
	v_mfma_f32_16x16x32_bf16 v[58:61], v[158:161], v[190:193], v[58:61]
	v_mfma_f32_16x16x32_bf16 v[54:57], v[150:153], v[186:189], v[54:57]
	v_mfma_f32_16x16x32_bf16 v[50:53], v[158:161], v[186:189], v[50:53]
	v_mfma_f32_16x16x32_bf16 v[46:49], v[150:153], v[182:185], v[46:49]
	v_mfma_f32_16x16x32_bf16 v[42:45], v[158:161], v[182:185], v[42:45]
	v_mfma_f32_16x16x32_bf16 v[38:41], v[150:153], v[178:181], v[38:41]
	v_mfma_f32_16x16x32_bf16 v[34:37], v[158:161], v[178:181], v[34:37]
	s_setprio 1
	s_setprio 0
	v_mfma_f32_16x16x32_bf16 v[30:33], v[130:133], v[174:177], v[30:33]
	v_mfma_f32_16x16x32_bf16 v[26:29], v[138:141], v[174:177], v[26:29]
	v_mfma_f32_16x16x32_bf16 v[22:25], v[130:133], v[170:173], v[22:25]
	v_mfma_f32_16x16x32_bf16 v[18:21], v[138:141], v[170:173], v[18:21]
	v_mfma_f32_16x16x32_bf16 v[14:17], v[130:133], v[166:169], v[14:17]
	v_mfma_f32_16x16x32_bf16 v[10:13], v[138:141], v[166:169], v[10:13]
	v_mfma_f32_16x16x32_bf16 v[6:9], v[130:133], v[162:165], v[6:9]
	v_mfma_f32_16x16x32_bf16 v[2:5], v[138:141], v[162:165], v[2:5]
	v_mfma_f32_16x16x32_bf16 v[30:33], v[134:137], v[190:193], v[30:33]
	v_mfma_f32_16x16x32_bf16 v[26:29], v[142:145], v[190:193], v[26:29]
	v_mfma_f32_16x16x32_bf16 v[22:25], v[134:137], v[186:189], v[22:25]
	v_mfma_f32_16x16x32_bf16 v[18:21], v[142:145], v[186:189], v[18:21]
	v_mfma_f32_16x16x32_bf16 v[14:17], v[134:137], v[182:185], v[14:17]
	v_mfma_f32_16x16x32_bf16 v[10:13], v[142:145], v[182:185], v[10:13]
	v_mfma_f32_16x16x32_bf16 v[6:9], v[134:137], v[178:181], v[6:9]
	v_mfma_f32_16x16x32_bf16 v[2:5], v[142:145], v[178:181], v[2:5]
	s_setprio 1
.LBB0_907:
	s_and_b64 vcc, s[40:41], s[72:73]
	v_cndmask_b32_e64 v131, v209, 0, vcc
	v_cndmask_b32_e32 v130, v208, v198, vcc
	v_lshl_add_u64 v[234:235], s[70:71], 0, v[130:131]
	s_barrier
	s_mov_b32 m0, s8
	s_nop 0
	global_load_lds_dwordx4 v194, s[98:99]
	s_mov_b32 m0, s13
	s_nop 0
	global_load_lds_dwordx4 v196, s[98:99]
	v_add_u32_e32 v130, 0x18000, v224
	v_add_u32_e32 v142, 0x1c000, v224
	ds_read_b128 v[146:149], v130
	ds_read_b128 v[150:153], v130 offset:1024
	ds_read_b128 v[154:157], v130 offset:2048
	ds_read_b128 v[158:161], v130 offset:3072
	ds_read_b128 v[130:133], v142
	ds_read_b128 v[134:137], v142 offset:1024
	ds_read_b128 v[138:141], v142 offset:2048
	ds_read_b128 v[142:145], v142 offset:3072
	s_mov_b32 m0, s14
	v_lshl_add_u64 v[236:237], v[234:235], 0, v[194:195]
	s_waitcnt lgkmcnt(0)
	ds_read_b128 v[174:177], v228 offset:32768
	ds_read_b128 v[190:193], v228 offset:33792
	ds_read_b128 v[170:173], v228 offset:34816
	ds_read_b128 v[186:189], v228 offset:35840
	ds_read_b128 v[166:169], v228 offset:36864
	ds_read_b128 v[182:185], v228 offset:37888
	ds_read_b128 v[162:165], v228 offset:38912
	ds_read_b128 v[178:181], v228 offset:39936
	global_load_lds_dwordx4 v[236:237], off
	v_lshl_add_u64 v[234:235], v[234:235], 0, v[196:197]
	s_mov_b32 m0, s15
	s_nop 0
	global_load_lds_dwordx4 v[234:235], off
	s_waitcnt vmcnt(8)
	s_waitcnt lgkmcnt(0)
	s_barrier
	s_setprio 0
	s_waitcnt lgkmcnt(0)
	v_mfma_f32_16x16x32_bf16 v[126:129], v[146:149], v[174:177], v[126:129]
	v_mfma_f32_16x16x32_bf16 v[122:125], v[154:157], v[174:177], v[122:125]
	v_mfma_f32_16x16x32_bf16 v[118:121], v[146:149], v[170:173], v[118:121]
	v_mfma_f32_16x16x32_bf16 v[114:117], v[154:157], v[170:173], v[114:117]
	v_mfma_f32_16x16x32_bf16 v[110:113], v[146:149], v[166:169], v[110:113]
	v_mfma_f32_16x16x32_bf16 v[106:109], v[154:157], v[166:169], v[106:109]
	v_mfma_f32_16x16x32_bf16 v[102:105], v[146:149], v[162:165], v[102:105]
	v_mfma_f32_16x16x32_bf16 v[98:101], v[154:157], v[162:165], v[98:101]
	v_mfma_f32_16x16x32_bf16 v[126:129], v[150:153], v[190:193], v[126:129]
	v_mfma_f32_16x16x32_bf16 v[122:125], v[158:161], v[190:193], v[122:125]
	v_mfma_f32_16x16x32_bf16 v[118:121], v[150:153], v[186:189], v[118:121]
	v_mfma_f32_16x16x32_bf16 v[114:117], v[158:161], v[186:189], v[114:117]
	v_mfma_f32_16x16x32_bf16 v[110:113], v[150:153], v[182:185], v[110:113]
	v_mfma_f32_16x16x32_bf16 v[106:109], v[158:161], v[182:185], v[106:109]
	v_mfma_f32_16x16x32_bf16 v[102:105], v[150:153], v[178:181], v[102:105]
	v_mfma_f32_16x16x32_bf16 v[98:101], v[158:161], v[178:181], v[98:101]
	s_setprio 1
	s_setprio 0
	v_mfma_f32_16x16x32_bf16 v[94:97], v[130:133], v[174:177], v[94:97]
	v_mfma_f32_16x16x32_bf16 v[90:93], v[138:141], v[174:177], v[90:93]
	v_mfma_f32_16x16x32_bf16 v[86:89], v[130:133], v[170:173], v[86:89]
	v_mfma_f32_16x16x32_bf16 v[82:85], v[138:141], v[170:173], v[82:85]
	v_mfma_f32_16x16x32_bf16 v[78:81], v[130:133], v[166:169], v[78:81]
	v_mfma_f32_16x16x32_bf16 v[74:77], v[138:141], v[166:169], v[74:77]
	v_mfma_f32_16x16x32_bf16 v[70:73], v[130:133], v[162:165], v[70:73]
	v_mfma_f32_16x16x32_bf16 v[66:69], v[138:141], v[162:165], v[66:69]
	v_mfma_f32_16x16x32_bf16 v[94:97], v[134:137], v[190:193], v[94:97]
	v_mfma_f32_16x16x32_bf16 v[90:93], v[142:145], v[190:193], v[90:93]
	v_mfma_f32_16x16x32_bf16 v[86:89], v[134:137], v[186:189], v[86:89]
	v_mfma_f32_16x16x32_bf16 v[82:85], v[142:145], v[186:189], v[82:85]
	v_mfma_f32_16x16x32_bf16 v[78:81], v[134:137], v[182:185], v[78:81]
	v_mfma_f32_16x16x32_bf16 v[74:77], v[142:145], v[182:185], v[74:77]
	v_mfma_f32_16x16x32_bf16 v[70:73], v[134:137], v[178:181], v[70:73]
	v_mfma_f32_16x16x32_bf16 v[66:69], v[142:145], v[178:181], v[66:69]
	s_setprio 1
	s_barrier
	s_and_b64 vcc, exec, s[42:43]
	s_cbranch_vccnz .LBB0_909
	ds_read_b128 v[174:177], v228 offset:49152
	ds_read_b128 v[190:193], v228 offset:50176
	ds_read_b128 v[170:173], v228 offset:51200
	ds_read_b128 v[186:189], v228 offset:52224
	ds_read_b128 v[166:169], v228 offset:53248
	ds_read_b128 v[182:185], v228 offset:54272
	ds_read_b128 v[162:165], v228 offset:55296
	ds_read_b128 v[178:181], v228 offset:56320
.LBB0_909:
	s_add_u32 s72, s68, 0xe0000
	s_addc_u32 s73, s69, 0
	s_add_u32 s70, s70, 0x220000
	s_addc_u32 s71, s71, 0
	s_mov_b32 m0, s16
	s_add_u32 s68, s68, 0xe4000
	global_load_lds_dwordx4 v194, s[72:73]
	s_mov_b32 m0, s17
	s_addc_u32 s69, s69, 0
	global_load_lds_dwordx4 v196, s[72:73]
	s_mov_b32 m0, s54
	s_and_b64 vcc, exec, s[42:43]
	global_load_lds_dwordx4 v194, s[68:69]
	s_mov_b32 m0, s55
	s_nop 0
	global_load_lds_dwordx4 v196, s[68:69]
	s_mov_b64 s[100:101], s[70:71]
	s_waitcnt vmcnt(6)
	s_waitcnt lgkmcnt(0)
	s_barrier
	s_cbranch_vccnz .LBB0_902
	s_setprio 0
	s_waitcnt lgkmcnt(0)
	v_mfma_f32_16x16x32_bf16 v[62:65], v[146:149], v[174:177], v[62:65]
	v_mfma_f32_16x16x32_bf16 v[58:61], v[154:157], v[174:177], v[58:61]
	v_mfma_f32_16x16x32_bf16 v[54:57], v[146:149], v[170:173], v[54:57]
	v_mfma_f32_16x16x32_bf16 v[50:53], v[154:157], v[170:173], v[50:53]
	v_mfma_f32_16x16x32_bf16 v[46:49], v[146:149], v[166:169], v[46:49]
	v_mfma_f32_16x16x32_bf16 v[42:45], v[154:157], v[166:169], v[42:45]
	v_mfma_f32_16x16x32_bf16 v[38:41], v[146:149], v[162:165], v[38:41]
	v_mfma_f32_16x16x32_bf16 v[34:37], v[154:157], v[162:165], v[34:37]
	v_mfma_f32_16x16x32_bf16 v[62:65], v[150:153], v[190:193], v[62:65]
	v_mfma_f32_16x16x32_bf16 v[58:61], v[158:161], v[190:193], v[58:61]
	v_mfma_f32_16x16x32_bf16 v[54:57], v[150:153], v[186:189], v[54:57]
	v_mfma_f32_16x16x32_bf16 v[50:53], v[158:161], v[186:189], v[50:53]
	v_mfma_f32_16x16x32_bf16 v[46:49], v[150:153], v[182:185], v[46:49]
	v_mfma_f32_16x16x32_bf16 v[42:45], v[158:161], v[182:185], v[42:45]
	v_mfma_f32_16x16x32_bf16 v[38:41], v[150:153], v[178:181], v[38:41]
	v_mfma_f32_16x16x32_bf16 v[34:37], v[158:161], v[178:181], v[34:37]
	s_setprio 1
	s_setprio 0
	v_mfma_f32_16x16x32_bf16 v[30:33], v[130:133], v[174:177], v[30:33]
	v_mfma_f32_16x16x32_bf16 v[26:29], v[138:141], v[174:177], v[26:29]
	v_mfma_f32_16x16x32_bf16 v[22:25], v[130:133], v[170:173], v[22:25]
	v_mfma_f32_16x16x32_bf16 v[18:21], v[138:141], v[170:173], v[18:21]
	v_mfma_f32_16x16x32_bf16 v[14:17], v[130:133], v[166:169], v[14:17]
	v_mfma_f32_16x16x32_bf16 v[10:13], v[138:141], v[166:169], v[10:13]
	v_mfma_f32_16x16x32_bf16 v[6:9], v[130:133], v[162:165], v[6:9]
	v_mfma_f32_16x16x32_bf16 v[2:5], v[138:141], v[162:165], v[2:5]
	v_mfma_f32_16x16x32_bf16 v[30:33], v[134:137], v[190:193], v[30:33]
	v_mfma_f32_16x16x32_bf16 v[26:29], v[142:145], v[190:193], v[26:29]
	v_mfma_f32_16x16x32_bf16 v[22:25], v[134:137], v[186:189], v[22:25]
	v_mfma_f32_16x16x32_bf16 v[18:21], v[142:145], v[186:189], v[18:21]
	v_mfma_f32_16x16x32_bf16 v[14:17], v[134:137], v[182:185], v[14:17]
	v_mfma_f32_16x16x32_bf16 v[10:13], v[142:145], v[182:185], v[10:13]
	v_mfma_f32_16x16x32_bf16 v[6:9], v[134:137], v[178:181], v[6:9]
	v_mfma_f32_16x16x32_bf16 v[2:5], v[142:145], v[178:181], v[2:5]
	s_setprio 1
	s_branch .LBB0_902

.LBB0_1289:
	s_mov_b32 m0, s27
	s_nop 0
	global_load_lds_dwordx4 v194, s[100:101]
	s_mov_b32 m0, s54
	s_nop 0
	global_load_lds_dwordx4 v196, s[100:101]
	v_add_u32_e32 v142, 0x14000, v229
	ds_read_b128 v[146:149], v230
	ds_read_b128 v[150:153], v230 offset:1024
	ds_read_b128 v[154:157], v230 offset:2048
	ds_read_b128 v[158:161], v230 offset:3072
	ds_read_b128 v[130:133], v142
	ds_read_b128 v[134:137], v142 offset:1024
	ds_read_b128 v[138:141], v142 offset:2048
	ds_read_b128 v[142:145], v142 offset:3072
	v_lshl_add_u64 v[234:235], v[222:223], 0, s[48:49]
	s_add_i32 m0, s8, 0xc000
	s_waitcnt lgkmcnt(0)
	ds_read_b128 v[174:177], v231
	ds_read_b128 v[190:193], v231 offset:1024
	ds_read_b128 v[170:173], v231 offset:2048
	ds_read_b128 v[186:189], v231 offset:3072
	ds_read_b128 v[166:169], v231 offset:4096
	ds_read_b128 v[182:185], v231 offset:5120
	ds_read_b128 v[162:165], v231 offset:6144
	ds_read_b128 v[178:181], v231 offset:7168
	global_load_lds_dwordx4 v[234:235], off
	v_lshl_add_u64 v[234:235], v[224:225], 0, s[48:49]
	s_add_i32 m0, s8, 0xe000
	s_nop 0
	global_load_lds_dwordx4 v[234:235], off
	s_waitcnt vmcnt(8)
	s_waitcnt lgkmcnt(0)
	s_barrier
	s_setprio 0
	s_waitcnt lgkmcnt(0)
	v_mfma_f32_16x16x32_bf16 v[126:129], v[146:149], v[174:177], v[126:129]
	v_mfma_f32_16x16x32_bf16 v[122:125], v[154:157], v[174:177], v[122:125]
	v_mfma_f32_16x16x32_bf16 v[118:121], v[146:149], v[170:173], v[118:121]
	v_mfma_f32_16x16x32_bf16 v[110:113], v[154:157], v[170:173], v[110:113]
	v_mfma_f32_16x16x32_bf16 v[102:105], v[146:149], v[166:169], v[102:105]
	v_mfma_f32_16x16x32_bf16 v[94:97], v[154:157], v[166:169], v[94:97]
	v_mfma_f32_16x16x32_bf16 v[86:89], v[146:149], v[162:165], v[86:89]
	v_mfma_f32_16x16x32_bf16 v[78:81], v[154:157], v[162:165], v[78:81]
	v_mfma_f32_16x16x32_bf16 v[126:129], v[150:153], v[190:193], v[126:129]
	v_mfma_f32_16x16x32_bf16 v[122:125], v[158:161], v[190:193], v[122:125]
	v_mfma_f32_16x16x32_bf16 v[118:121], v[150:153], v[186:189], v[118:121]
	v_mfma_f32_16x16x32_bf16 v[110:113], v[158:161], v[186:189], v[110:113]
	v_mfma_f32_16x16x32_bf16 v[102:105], v[150:153], v[182:185], v[102:105]
	v_mfma_f32_16x16x32_bf16 v[94:97], v[158:161], v[182:185], v[94:97]
	v_mfma_f32_16x16x32_bf16 v[86:89], v[150:153], v[178:181], v[86:89]
	v_mfma_f32_16x16x32_bf16 v[78:81], v[158:161], v[178:181], v[78:81]
	s_setprio 1
	s_setprio 0
	v_mfma_f32_16x16x32_bf16 v[114:117], v[130:133], v[174:177], v[114:117]
	v_mfma_f32_16x16x32_bf16 v[106:109], v[138:141], v[174:177], v[106:109]
	v_mfma_f32_16x16x32_bf16 v[98:101], v[130:133], v[170:173], v[98:101]
	v_mfma_f32_16x16x32_bf16 v[90:93], v[138:141], v[170:173], v[90:93]
	v_mfma_f32_16x16x32_bf16 v[82:85], v[130:133], v[166:169], v[82:85]
	v_mfma_f32_16x16x32_bf16 v[74:77], v[138:141], v[166:169], v[74:77]
	v_mfma_f32_16x16x32_bf16 v[70:73], v[130:133], v[162:165], v[70:73]
	v_mfma_f32_16x16x32_bf16 v[66:69], v[138:141], v[162:165], v[66:69]
	v_mfma_f32_16x16x32_bf16 v[114:117], v[134:137], v[190:193], v[114:117]
	v_mfma_f32_16x16x32_bf16 v[106:109], v[142:145], v[190:193], v[106:109]
	v_mfma_f32_16x16x32_bf16 v[98:101], v[134:137], v[186:189], v[98:101]
	v_mfma_f32_16x16x32_bf16 v[90:93], v[142:145], v[186:189], v[90:93]
	v_mfma_f32_16x16x32_bf16 v[82:85], v[134:137], v[182:185], v[82:85]
	v_mfma_f32_16x16x32_bf16 v[74:77], v[142:145], v[182:185], v[74:77]
	v_mfma_f32_16x16x32_bf16 v[70:73], v[134:137], v[178:181], v[70:73]
	v_mfma_f32_16x16x32_bf16 v[66:69], v[142:145], v[178:181], v[66:69]
	s_setprio 1
	s_barrier
	v_cndmask_b32_e64 v233, 0, 1, s[40:41]
	v_cmp_ne_u32_e64 s[42:43], 1, v233
	s_andn2_b64 vcc, exec, s[40:41]
	s_cbranch_vccnz .LBB0_1291
	ds_read_b128 v[174:177], v231 offset:16384
	ds_read_b128 v[190:193], v231 offset:17408
	ds_read_b128 v[170:173], v231 offset:18432
	ds_read_b128 v[186:189], v231 offset:19456
	ds_read_b128 v[166:169], v231 offset:20480
	ds_read_b128 v[182:185], v231 offset:21504
	ds_read_b128 v[162:165], v231 offset:22528
	ds_read_b128 v[178:181], v231 offset:23552
.LBB0_1291:
	s_add_u32 s52, s36, s48
	s_addc_u32 s53, s37, s49
	s_add_u32 s56, s52, 0x440000
	s_addc_u32 s57, s53, 0
	s_cmp_eq_u32 s48, 0x3fc0000
	s_cselect_b64 s[58:59], -1, 0
	s_and_b64 s[52:53], s[58:59], exec
	s_cselect_b32 s53, s31, s63
	s_cselect_b32 s52, s61, s62
	s_mov_b32 m0, s9
	s_cselect_b32 s57, s19, s57
	s_cselect_b32 s56, s29, s56
	s_add_u32 s68, s52, 0x4000
	global_load_lds_dwordx4 v194, s[52:53]
	s_mov_b32 m0, s10
	s_addc_u32 s69, s53, 0
	global_load_lds_dwordx4 v196, s[52:53]
	s_mov_b32 m0, s11
	s_and_b64 vcc, exec, s[42:43]
	global_load_lds_dwordx4 v194, s[68:69]
	s_mov_b32 m0, s12
	s_nop 0
	global_load_lds_dwordx4 v196, s[68:69]
	s_mov_b64 s[98:99], s[56:57]
	s_waitcnt vmcnt(6)
	s_waitcnt lgkmcnt(0)
	s_barrier
	s_cbranch_vccnz .LBB0_1293
	s_setprio 0
	s_waitcnt lgkmcnt(0)
	v_mfma_f32_16x16x32_bf16 v[62:65], v[146:149], v[174:177], v[62:65]
	v_mfma_f32_16x16x32_bf16 v[58:61], v[154:157], v[174:177], v[58:61]
	v_mfma_f32_16x16x32_bf16 v[46:49], v[146:149], v[170:173], v[46:49]
	v_mfma_f32_16x16x32_bf16 v[42:45], v[154:157], v[170:173], v[42:45]
	v_mfma_f32_16x16x32_bf16 v[30:33], v[146:149], v[166:169], v[30:33]
	v_mfma_f32_16x16x32_bf16 v[26:29], v[154:157], v[166:169], v[26:29]
	v_mfma_f32_16x16x32_bf16 v[14:17], v[146:149], v[162:165], v[14:17]
	v_mfma_f32_16x16x32_bf16 v[10:13], v[154:157], v[162:165], v[10:13]
	v_mfma_f32_16x16x32_bf16 v[62:65], v[150:153], v[190:193], v[62:65]
	v_mfma_f32_16x16x32_bf16 v[58:61], v[158:161], v[190:193], v[58:61]
	v_mfma_f32_16x16x32_bf16 v[46:49], v[150:153], v[186:189], v[46:49]
	v_mfma_f32_16x16x32_bf16 v[42:45], v[158:161], v[186:189], v[42:45]
	v_mfma_f32_16x16x32_bf16 v[30:33], v[150:153], v[182:185], v[30:33]
	v_mfma_f32_16x16x32_bf16 v[26:29], v[158:161], v[182:185], v[26:29]
	v_mfma_f32_16x16x32_bf16 v[14:17], v[150:153], v[178:181], v[14:17]
	v_mfma_f32_16x16x32_bf16 v[10:13], v[158:161], v[178:181], v[10:13]
	s_setprio 1
	s_setprio 0
	v_mfma_f32_16x16x32_bf16 v[54:57], v[130:133], v[174:177], v[54:57]
	v_mfma_f32_16x16x32_bf16 v[50:53], v[138:141], v[174:177], v[50:53]
	v_mfma_f32_16x16x32_bf16 v[38:41], v[130:133], v[170:173], v[38:41]
	v_mfma_f32_16x16x32_bf16 v[34:37], v[138:141], v[170:173], v[34:37]
	v_mfma_f32_16x16x32_bf16 v[22:25], v[130:133], v[166:169], v[22:25]
	v_mfma_f32_16x16x32_bf16 v[18:21], v[138:141], v[166:169], v[18:21]
	v_mfma_f32_16x16x32_bf16 v[6:9], v[130:133], v[162:165], v[6:9]
	v_mfma_f32_16x16x32_bf16 v[2:5], v[138:141], v[162:165], v[2:5]
	v_mfma_f32_16x16x32_bf16 v[54:57], v[134:137], v[190:193], v[54:57]
	v_mfma_f32_16x16x32_bf16 v[50:53], v[142:145], v[190:193], v[50:53]
	v_mfma_f32_16x16x32_bf16 v[38:41], v[134:137], v[186:189], v[38:41]
	v_mfma_f32_16x16x32_bf16 v[34:37], v[142:145], v[186:189], v[34:37]
	v_mfma_f32_16x16x32_bf16 v[22:25], v[134:137], v[182:185], v[22:25]
	v_mfma_f32_16x16x32_bf16 v[18:21], v[142:145], v[182:185], v[18:21]
	v_mfma_f32_16x16x32_bf16 v[6:9], v[134:137], v[178:181], v[6:9]
	v_mfma_f32_16x16x32_bf16 v[2:5], v[142:145], v[178:181], v[2:5]
	s_setprio 1
.LBB0_1293:
	s_and_b64 vcc, s[34:35], s[58:59]
	v_cndmask_b32_e64 v131, v221, 0, vcc
	v_cndmask_b32_e32 v130, v220, v198, vcc
	v_lshl_add_u64 v[234:235], s[56:57], 0, v[130:131]
	s_barrier
	s_mov_b32 m0, s8
	s_nop 0
	global_load_lds_dwordx4 v194, s[98:99]
	s_mov_b32 m0, s13
	s_nop 0
	global_load_lds_dwordx4 v196, s[98:99]
	v_add_u32_e32 v130, 0x18000, v229
	v_add_u32_e32 v142, 0x1c000, v229
	ds_read_b128 v[146:149], v130
	ds_read_b128 v[150:153], v130 offset:1024
	ds_read_b128 v[154:157], v130 offset:2048
	ds_read_b128 v[158:161], v130 offset:3072
	ds_read_b128 v[130:133], v142
	ds_read_b128 v[134:137], v142 offset:1024
	ds_read_b128 v[138:141], v142 offset:2048
	ds_read_b128 v[142:145], v142 offset:3072
	s_mov_b32 m0, s14
	v_lshl_add_u64 v[236:237], v[234:235], 0, v[194:195]
	s_waitcnt lgkmcnt(0)
	ds_read_b128 v[174:177], v231 offset:32768
	ds_read_b128 v[190:193], v231 offset:33792
	ds_read_b128 v[170:173], v231 offset:34816
	ds_read_b128 v[186:189], v231 offset:35840
	ds_read_b128 v[166:169], v231 offset:36864
	ds_read_b128 v[182:185], v231 offset:37888
	ds_read_b128 v[162:165], v231 offset:38912
	ds_read_b128 v[178:181], v231 offset:39936
	global_load_lds_dwordx4 v[236:237], off
	v_lshl_add_u64 v[234:235], v[234:235], 0, v[196:197]
	s_mov_b32 m0, s15
	s_nop 0
	global_load_lds_dwordx4 v[234:235], off
	s_waitcnt vmcnt(8)
	s_waitcnt lgkmcnt(0)
	s_barrier
	s_setprio 0
	s_waitcnt lgkmcnt(0)
	v_mfma_f32_16x16x32_bf16 v[126:129], v[146:149], v[174:177], v[126:129]
	v_mfma_f32_16x16x32_bf16 v[122:125], v[154:157], v[174:177], v[122:125]
	v_mfma_f32_16x16x32_bf16 v[118:121], v[146:149], v[170:173], v[118:121]
	v_mfma_f32_16x16x32_bf16 v[110:113], v[154:157], v[170:173], v[110:113]
	v_mfma_f32_16x16x32_bf16 v[102:105], v[146:149], v[166:169], v[102:105]
	v_mfma_f32_16x16x32_bf16 v[94:97], v[154:157], v[166:169], v[94:97]
	v_mfma_f32_16x16x32_bf16 v[86:89], v[146:149], v[162:165], v[86:89]
	v_mfma_f32_16x16x32_bf16 v[78:81], v[154:157], v[162:165], v[78:81]
	v_mfma_f32_16x16x32_bf16 v[126:129], v[150:153], v[190:193], v[126:129]
	v_mfma_f32_16x16x32_bf16 v[122:125], v[158:161], v[190:193], v[122:125]
	v_mfma_f32_16x16x32_bf16 v[118:121], v[150:153], v[186:189], v[118:121]
	v_mfma_f32_16x16x32_bf16 v[110:113], v[158:161], v[186:189], v[110:113]
	v_mfma_f32_16x16x32_bf16 v[102:105], v[150:153], v[182:185], v[102:105]
	v_mfma_f32_16x16x32_bf16 v[94:97], v[158:161], v[182:185], v[94:97]
	v_mfma_f32_16x16x32_bf16 v[86:89], v[150:153], v[178:181], v[86:89]
	v_mfma_f32_16x16x32_bf16 v[78:81], v[158:161], v[178:181], v[78:81]
	s_setprio 1
	s_setprio 0
	v_mfma_f32_16x16x32_bf16 v[114:117], v[130:133], v[174:177], v[114:117]
	v_mfma_f32_16x16x32_bf16 v[106:109], v[138:141], v[174:177], v[106:109]
	v_mfma_f32_16x16x32_bf16 v[98:101], v[130:133], v[170:173], v[98:101]
	v_mfma_f32_16x16x32_bf16 v[90:93], v[138:141], v[170:173], v[90:93]
	v_mfma_f32_16x16x32_bf16 v[82:85], v[130:133], v[166:169], v[82:85]
	v_mfma_f32_16x16x32_bf16 v[74:77], v[138:141], v[166:169], v[74:77]
	v_mfma_f32_16x16x32_bf16 v[70:73], v[130:133], v[162:165], v[70:73]
	v_mfma_f32_16x16x32_bf16 v[66:69], v[138:141], v[162:165], v[66:69]
	v_mfma_f32_16x16x32_bf16 v[114:117], v[134:137], v[190:193], v[114:117]
	v_mfma_f32_16x16x32_bf16 v[106:109], v[142:145], v[190:193], v[106:109]
	v_mfma_f32_16x16x32_bf16 v[98:101], v[134:137], v[186:189], v[98:101]
	v_mfma_f32_16x16x32_bf16 v[90:93], v[142:145], v[186:189], v[90:93]
	v_mfma_f32_16x16x32_bf16 v[82:85], v[134:137], v[182:185], v[82:85]
	v_mfma_f32_16x16x32_bf16 v[74:77], v[142:145], v[182:185], v[74:77]
	v_mfma_f32_16x16x32_bf16 v[70:73], v[134:137], v[178:181], v[70:73]
	v_mfma_f32_16x16x32_bf16 v[66:69], v[142:145], v[178:181], v[66:69]
	s_setprio 1
	s_barrier
	s_and_b64 vcc, exec, s[42:43]
	s_cbranch_vccnz .LBB0_1295
	ds_read_b128 v[174:177], v231 offset:49152
	ds_read_b128 v[190:193], v231 offset:50176
	ds_read_b128 v[170:173], v231 offset:51200
	ds_read_b128 v[186:189], v231 offset:52224
	ds_read_b128 v[166:169], v231 offset:53248
	ds_read_b128 v[182:185], v231 offset:54272
	ds_read_b128 v[162:165], v231 offset:55296
	ds_read_b128 v[178:181], v231 offset:56320
.LBB0_1295:
	s_add_u32 s58, s52, 0x40000
	s_addc_u32 s59, s53, 0
	s_add_u32 s56, s56, 0x220000
	s_addc_u32 s57, s57, 0
	s_mov_b32 m0, s16
	s_add_u32 s52, s52, 0x44000
	global_load_lds_dwordx4 v194, s[58:59]
	s_mov_b32 m0, s17
	s_addc_u32 s53, s53, 0
	global_load_lds_dwordx4 v196, s[58:59]
	s_mov_b32 m0, s55
	s_and_b64 vcc, exec, s[42:43]
	global_load_lds_dwordx4 v194, s[52:53]
	s_mov_b32 m0, s60
	s_nop 0
	global_load_lds_dwordx4 v196, s[52:53]
	s_mov_b64 s[100:101], s[56:57]
	s_waitcnt vmcnt(6)
	s_waitcnt lgkmcnt(0)
	s_barrier
	s_cbranch_vccnz .LBB0_1288
	s_setprio 0
	s_waitcnt lgkmcnt(0)
	v_mfma_f32_16x16x32_bf16 v[62:65], v[146:149], v[174:177], v[62:65]
	v_mfma_f32_16x16x32_bf16 v[58:61], v[154:157], v[174:177], v[58:61]
	v_mfma_f32_16x16x32_bf16 v[46:49], v[146:149], v[170:173], v[46:49]
	v_mfma_f32_16x16x32_bf16 v[42:45], v[154:157], v[170:173], v[42:45]
	v_mfma_f32_16x16x32_bf16 v[30:33], v[146:149], v[166:169], v[30:33]
	v_mfma_f32_16x16x32_bf16 v[26:29], v[154:157], v[166:169], v[26:29]
	v_mfma_f32_16x16x32_bf16 v[14:17], v[146:149], v[162:165], v[14:17]
	v_mfma_f32_16x16x32_bf16 v[10:13], v[154:157], v[162:165], v[10:13]
	v_mfma_f32_16x16x32_bf16 v[62:65], v[150:153], v[190:193], v[62:65]
	v_mfma_f32_16x16x32_bf16 v[58:61], v[158:161], v[190:193], v[58:61]
	v_mfma_f32_16x16x32_bf16 v[46:49], v[150:153], v[186:189], v[46:49]
	v_mfma_f32_16x16x32_bf16 v[42:45], v[158:161], v[186:189], v[42:45]
	v_mfma_f32_16x16x32_bf16 v[30:33], v[150:153], v[182:185], v[30:33]
	v_mfma_f32_16x16x32_bf16 v[26:29], v[158:161], v[182:185], v[26:29]
	v_mfma_f32_16x16x32_bf16 v[14:17], v[150:153], v[178:181], v[14:17]
	v_mfma_f32_16x16x32_bf16 v[10:13], v[158:161], v[178:181], v[10:13]
	s_setprio 1
	s_setprio 0
	v_mfma_f32_16x16x32_bf16 v[54:57], v[130:133], v[174:177], v[54:57]
	v_mfma_f32_16x16x32_bf16 v[50:53], v[138:141], v[174:177], v[50:53]
	v_mfma_f32_16x16x32_bf16 v[38:41], v[130:133], v[170:173], v[38:41]
	v_mfma_f32_16x16x32_bf16 v[34:37], v[138:141], v[170:173], v[34:37]
	v_mfma_f32_16x16x32_bf16 v[22:25], v[130:133], v[166:169], v[22:25]
	v_mfma_f32_16x16x32_bf16 v[18:21], v[138:141], v[166:169], v[18:21]
	v_mfma_f32_16x16x32_bf16 v[6:9], v[130:133], v[162:165], v[6:9]
	v_mfma_f32_16x16x32_bf16 v[2:5], v[138:141], v[162:165], v[2:5]
	v_mfma_f32_16x16x32_bf16 v[54:57], v[134:137], v[190:193], v[54:57]
	v_mfma_f32_16x16x32_bf16 v[50:53], v[142:145], v[190:193], v[50:53]
	v_mfma_f32_16x16x32_bf16 v[38:41], v[134:137], v[186:189], v[38:41]
	v_mfma_f32_16x16x32_bf16 v[34:37], v[142:145], v[186:189], v[34:37]
	v_mfma_f32_16x16x32_bf16 v[22:25], v[134:137], v[182:185], v[22:25]
	v_mfma_f32_16x16x32_bf16 v[18:21], v[142:145], v[182:185], v[18:21]
	v_mfma_f32_16x16x32_bf16 v[6:9], v[134:137], v[178:181], v[6:9]
	v_mfma_f32_16x16x32_bf16 v[2:5], v[142:145], v[178:181], v[2:5]
	s_setprio 1
	s_branch .LBB0_1288

.LBB0_1612:
	s_mov_b32 m0, s54
	s_nop 0
	global_load_lds_dwordx4 v194, s[100:101]
	s_mov_b32 m0, s55
	s_nop 0
	global_load_lds_dwordx4 v196, s[100:101]
	v_add_u32_e32 v1, 0x10000, v232
	ds_read_b128 v[146:149], v1
	ds_read_b128 v[150:153], v1 offset:1024
	ds_read_b128 v[154:157], v1 offset:2048
	ds_read_b128 v[158:161], v1 offset:3072
	v_add_u32_e32 v1, 0x14000, v232
	ds_read_b128 v[130:133], v1
	ds_read_b128 v[134:137], v1 offset:1024
	ds_read_b128 v[138:141], v1 offset:2048
	ds_read_b128 v[142:145], v1 offset:3072
	v_lshl_add_u64 v[236:237], v[226:227], 0, s[48:49]
	s_add_i32 m0, s9, 0xc000
	s_waitcnt lgkmcnt(0)
	ds_read_b128 v[174:177], v233
	ds_read_b128 v[190:193], v233 offset:1024
	ds_read_b128 v[170:173], v233 offset:2048
	ds_read_b128 v[186:189], v233 offset:3072
	ds_read_b128 v[166:169], v233 offset:4096
	ds_read_b128 v[182:185], v233 offset:5120
	ds_read_b128 v[162:165], v233 offset:6144
	ds_read_b128 v[178:181], v233 offset:7168
	global_load_lds_dwordx4 v[236:237], off
	v_lshl_add_u64 v[236:237], v[228:229], 0, s[48:49]
	s_add_i32 m0, s9, 0xe000
	s_nop 0
	global_load_lds_dwordx4 v[236:237], off
	s_waitcnt vmcnt(8)
	s_waitcnt lgkmcnt(0)
	s_barrier
	s_setprio 0
	s_waitcnt lgkmcnt(0)
	v_mfma_f32_16x16x32_bf16 v[126:129], v[146:149], v[174:177], v[126:129]
	v_mfma_f32_16x16x32_bf16 v[122:125], v[154:157], v[174:177], v[122:125]
	v_mfma_f32_16x16x32_bf16 v[118:121], v[146:149], v[170:173], v[118:121]
	v_mfma_f32_16x16x32_bf16 v[110:113], v[154:157], v[170:173], v[110:113]
	v_mfma_f32_16x16x32_bf16 v[102:105], v[146:149], v[166:169], v[102:105]
	v_mfma_f32_16x16x32_bf16 v[94:97], v[154:157], v[166:169], v[94:97]
	v_mfma_f32_16x16x32_bf16 v[86:89], v[146:149], v[162:165], v[86:89]
	v_mfma_f32_16x16x32_bf16 v[78:81], v[154:157], v[162:165], v[78:81]
	v_mfma_f32_16x16x32_bf16 v[126:129], v[150:153], v[190:193], v[126:129]
	v_mfma_f32_16x16x32_bf16 v[122:125], v[158:161], v[190:193], v[122:125]
	v_mfma_f32_16x16x32_bf16 v[118:121], v[150:153], v[186:189], v[118:121]
	v_mfma_f32_16x16x32_bf16 v[110:113], v[158:161], v[186:189], v[110:113]
	v_mfma_f32_16x16x32_bf16 v[102:105], v[150:153], v[182:185], v[102:105]
	v_mfma_f32_16x16x32_bf16 v[94:97], v[158:161], v[182:185], v[94:97]
	v_mfma_f32_16x16x32_bf16 v[86:89], v[150:153], v[178:181], v[86:89]
	v_mfma_f32_16x16x32_bf16 v[78:81], v[158:161], v[178:181], v[78:81]
	s_setprio 1
	s_setprio 0
	v_mfma_f32_16x16x32_bf16 v[114:117], v[130:133], v[174:177], v[114:117]
	v_mfma_f32_16x16x32_bf16 v[106:109], v[138:141], v[174:177], v[106:109]
	v_mfma_f32_16x16x32_bf16 v[98:101], v[130:133], v[170:173], v[98:101]
	v_mfma_f32_16x16x32_bf16 v[90:93], v[138:141], v[170:173], v[90:93]
	v_mfma_f32_16x16x32_bf16 v[82:85], v[130:133], v[166:169], v[82:85]
	v_mfma_f32_16x16x32_bf16 v[74:77], v[138:141], v[166:169], v[74:77]
	v_mfma_f32_16x16x32_bf16 v[70:73], v[130:133], v[162:165], v[70:73]
	v_mfma_f32_16x16x32_bf16 v[66:69], v[138:141], v[162:165], v[66:69]
	v_mfma_f32_16x16x32_bf16 v[114:117], v[134:137], v[190:193], v[114:117]
	v_mfma_f32_16x16x32_bf16 v[106:109], v[142:145], v[190:193], v[106:109]
	v_mfma_f32_16x16x32_bf16 v[98:101], v[134:137], v[186:189], v[98:101]
	v_mfma_f32_16x16x32_bf16 v[90:93], v[142:145], v[186:189], v[90:93]
	v_mfma_f32_16x16x32_bf16 v[82:85], v[134:137], v[182:185], v[82:85]
	v_mfma_f32_16x16x32_bf16 v[74:77], v[142:145], v[182:185], v[74:77]
	v_mfma_f32_16x16x32_bf16 v[70:73], v[134:137], v[178:181], v[70:73]
	v_mfma_f32_16x16x32_bf16 v[66:69], v[142:145], v[178:181], v[66:69]
	s_setprio 1
	s_barrier
	v_cndmask_b32_e64 v1, 0, 1, s[40:41]
	v_cmp_ne_u32_e64 s[42:43], 1, v1
	s_andn2_b64 vcc, exec, s[40:41]
	s_cbranch_vccnz .LBB0_1614
	ds_read_b128 v[174:177], v233 offset:16384
	ds_read_b128 v[190:193], v233 offset:17408
	ds_read_b128 v[170:173], v233 offset:18432
	ds_read_b128 v[186:189], v233 offset:19456
	ds_read_b128 v[166:169], v233 offset:20480
	ds_read_b128 v[182:185], v233 offset:21504
	ds_read_b128 v[162:165], v233 offset:22528
	ds_read_b128 v[178:181], v233 offset:23552
.LBB0_1614:
	s_add_u32 s50, s46, s48
	s_addc_u32 s51, s47, s49
	s_add_u32 s52, s50, 0x440000
	s_addc_u32 s53, s51, 0
	s_cmp_eq_u32 s48, 0x3fc0000
	s_cselect_b64 s[56:57], -1, 0
	s_and_b64 s[50:51], s[56:57], exec
	s_cselect_b32 s51, s31, s61
	s_cselect_b32 s50, s35, s60
	s_mov_b32 m0, s10
	s_cselect_b32 s53, s19, s53
	s_cselect_b32 s52, s20, s52
	s_add_u32 s68, s50, 0x4000
	global_load_lds_dwordx4 v194, s[50:51]
	s_mov_b32 m0, s11
	s_addc_u32 s69, s51, 0
	global_load_lds_dwordx4 v196, s[50:51]
	s_mov_b32 m0, s12
	s_and_b64 vcc, exec, s[42:43]
	global_load_lds_dwordx4 v194, s[68:69]
	s_mov_b32 m0, s13
	s_nop 0
	global_load_lds_dwordx4 v196, s[68:69]
	s_mov_b64 s[98:99], s[52:53]
	s_waitcnt vmcnt(6)
	s_waitcnt lgkmcnt(0)
	s_barrier
	s_cbranch_vccnz .LBB0_1616
	s_setprio 0
	s_waitcnt lgkmcnt(0)
	v_mfma_f32_16x16x32_bf16 v[62:65], v[146:149], v[174:177], v[62:65]
	v_mfma_f32_16x16x32_bf16 v[58:61], v[154:157], v[174:177], v[58:61]
	v_mfma_f32_16x16x32_bf16 v[46:49], v[146:149], v[170:173], v[46:49]
	v_mfma_f32_16x16x32_bf16 v[42:45], v[154:157], v[170:173], v[42:45]
	v_mfma_f32_16x16x32_bf16 v[30:33], v[146:149], v[166:169], v[30:33]
	v_mfma_f32_16x16x32_bf16 v[26:29], v[154:157], v[166:169], v[26:29]
	v_mfma_f32_16x16x32_bf16 v[14:17], v[146:149], v[162:165], v[14:17]
	v_mfma_f32_16x16x32_bf16 v[10:13], v[154:157], v[162:165], v[10:13]
	v_mfma_f32_16x16x32_bf16 v[62:65], v[150:153], v[190:193], v[62:65]
	v_mfma_f32_16x16x32_bf16 v[58:61], v[158:161], v[190:193], v[58:61]
	v_mfma_f32_16x16x32_bf16 v[46:49], v[150:153], v[186:189], v[46:49]
	v_mfma_f32_16x16x32_bf16 v[42:45], v[158:161], v[186:189], v[42:45]
	v_mfma_f32_16x16x32_bf16 v[30:33], v[150:153], v[182:185], v[30:33]
	v_mfma_f32_16x16x32_bf16 v[26:29], v[158:161], v[182:185], v[26:29]
	v_mfma_f32_16x16x32_bf16 v[14:17], v[150:153], v[178:181], v[14:17]
	v_mfma_f32_16x16x32_bf16 v[10:13], v[158:161], v[178:181], v[10:13]
	s_setprio 1
	s_setprio 0
	v_mfma_f32_16x16x32_bf16 v[54:57], v[130:133], v[174:177], v[54:57]
	v_mfma_f32_16x16x32_bf16 v[50:53], v[138:141], v[174:177], v[50:53]
	v_mfma_f32_16x16x32_bf16 v[38:41], v[130:133], v[170:173], v[38:41]
	v_mfma_f32_16x16x32_bf16 v[34:37], v[138:141], v[170:173], v[34:37]
	v_mfma_f32_16x16x32_bf16 v[22:25], v[130:133], v[166:169], v[22:25]
	v_mfma_f32_16x16x32_bf16 v[18:21], v[138:141], v[166:169], v[18:21]
	v_mfma_f32_16x16x32_bf16 v[6:9], v[130:133], v[162:165], v[6:9]
	v_mfma_f32_16x16x32_bf16 v[2:5], v[138:141], v[162:165], v[2:5]
	v_mfma_f32_16x16x32_bf16 v[54:57], v[134:137], v[190:193], v[54:57]
	v_mfma_f32_16x16x32_bf16 v[50:53], v[142:145], v[190:193], v[50:53]
	v_mfma_f32_16x16x32_bf16 v[38:41], v[134:137], v[186:189], v[38:41]
	v_mfma_f32_16x16x32_bf16 v[34:37], v[142:145], v[186:189], v[34:37]
	v_mfma_f32_16x16x32_bf16 v[22:25], v[134:137], v[182:185], v[22:25]
	v_mfma_f32_16x16x32_bf16 v[18:21], v[142:145], v[182:185], v[18:21]
	v_mfma_f32_16x16x32_bf16 v[6:9], v[134:137], v[178:181], v[6:9]
	v_mfma_f32_16x16x32_bf16 v[2:5], v[142:145], v[178:181], v[2:5]
	s_setprio 1
.LBB0_1616:
	s_and_b64 vcc, s[38:39], s[56:57]
	v_cndmask_b32_e64 v131, v225, 0, vcc
	v_cndmask_b32_e32 v130, v224, v198, vcc
	v_lshl_add_u64 v[236:237], s[52:53], 0, v[130:131]
	s_barrier
	s_mov_b32 m0, s9
	s_nop 0
	global_load_lds_dwordx4 v194, s[98:99]
	s_mov_b32 m0, s14
	s_nop 0
	global_load_lds_dwordx4 v196, s[98:99]
	v_add_u32_e32 v1, 0x18000, v232
	ds_read_b128 v[146:149], v1
	ds_read_b128 v[150:153], v1 offset:1024
	ds_read_b128 v[154:157], v1 offset:2048
	ds_read_b128 v[158:161], v1 offset:3072
	v_add_u32_e32 v1, 0x1c000, v232
	ds_read_b128 v[130:133], v1
	ds_read_b128 v[134:137], v1 offset:1024
	ds_read_b128 v[138:141], v1 offset:2048
	ds_read_b128 v[142:145], v1 offset:3072
	s_mov_b32 m0, s15
	v_lshl_add_u64 v[238:239], v[236:237], 0, v[194:195]
	s_waitcnt lgkmcnt(0)
	ds_read_b128 v[174:177], v233 offset:32768
	ds_read_b128 v[190:193], v233 offset:33792
	ds_read_b128 v[170:173], v233 offset:34816
	ds_read_b128 v[186:189], v233 offset:35840
	ds_read_b128 v[166:169], v233 offset:36864
	ds_read_b128 v[182:185], v233 offset:37888
	ds_read_b128 v[162:165], v233 offset:38912
	ds_read_b128 v[178:181], v233 offset:39936
	global_load_lds_dwordx4 v[238:239], off
	v_lshl_add_u64 v[236:237], v[236:237], 0, v[196:197]
	s_mov_b32 m0, s16
	s_nop 0
	global_load_lds_dwordx4 v[236:237], off
	s_waitcnt vmcnt(8)
	s_waitcnt lgkmcnt(0)
	s_barrier
	s_setprio 0
	s_waitcnt lgkmcnt(0)
	v_mfma_f32_16x16x32_bf16 v[126:129], v[146:149], v[174:177], v[126:129]
	v_mfma_f32_16x16x32_bf16 v[122:125], v[154:157], v[174:177], v[122:125]
	v_mfma_f32_16x16x32_bf16 v[118:121], v[146:149], v[170:173], v[118:121]
	v_mfma_f32_16x16x32_bf16 v[110:113], v[154:157], v[170:173], v[110:113]
	v_mfma_f32_16x16x32_bf16 v[102:105], v[146:149], v[166:169], v[102:105]
	v_mfma_f32_16x16x32_bf16 v[94:97], v[154:157], v[166:169], v[94:97]
	v_mfma_f32_16x16x32_bf16 v[86:89], v[146:149], v[162:165], v[86:89]
	v_mfma_f32_16x16x32_bf16 v[78:81], v[154:157], v[162:165], v[78:81]
	v_mfma_f32_16x16x32_bf16 v[126:129], v[150:153], v[190:193], v[126:129]
	v_mfma_f32_16x16x32_bf16 v[122:125], v[158:161], v[190:193], v[122:125]
	v_mfma_f32_16x16x32_bf16 v[118:121], v[150:153], v[186:189], v[118:121]
	v_mfma_f32_16x16x32_bf16 v[110:113], v[158:161], v[186:189], v[110:113]
	v_mfma_f32_16x16x32_bf16 v[102:105], v[150:153], v[182:185], v[102:105]
	v_mfma_f32_16x16x32_bf16 v[94:97], v[158:161], v[182:185], v[94:97]
	v_mfma_f32_16x16x32_bf16 v[86:89], v[150:153], v[178:181], v[86:89]
	v_mfma_f32_16x16x32_bf16 v[78:81], v[158:161], v[178:181], v[78:81]
	s_setprio 1
	s_setprio 0
	v_mfma_f32_16x16x32_bf16 v[114:117], v[130:133], v[174:177], v[114:117]
	v_mfma_f32_16x16x32_bf16 v[106:109], v[138:141], v[174:177], v[106:109]
	v_mfma_f32_16x16x32_bf16 v[98:101], v[130:133], v[170:173], v[98:101]
	v_mfma_f32_16x16x32_bf16 v[90:93], v[138:141], v[170:173], v[90:93]
	v_mfma_f32_16x16x32_bf16 v[82:85], v[130:133], v[166:169], v[82:85]
	v_mfma_f32_16x16x32_bf16 v[74:77], v[138:141], v[166:169], v[74:77]
	v_mfma_f32_16x16x32_bf16 v[70:73], v[130:133], v[162:165], v[70:73]
	v_mfma_f32_16x16x32_bf16 v[66:69], v[138:141], v[162:165], v[66:69]
	v_mfma_f32_16x16x32_bf16 v[114:117], v[134:137], v[190:193], v[114:117]
	v_mfma_f32_16x16x32_bf16 v[106:109], v[142:145], v[190:193], v[106:109]
	v_mfma_f32_16x16x32_bf16 v[98:101], v[134:137], v[186:189], v[98:101]
	v_mfma_f32_16x16x32_bf16 v[90:93], v[142:145], v[186:189], v[90:93]
	v_mfma_f32_16x16x32_bf16 v[82:85], v[134:137], v[182:185], v[82:85]
	v_mfma_f32_16x16x32_bf16 v[74:77], v[142:145], v[182:185], v[74:77]
	v_mfma_f32_16x16x32_bf16 v[70:73], v[134:137], v[178:181], v[70:73]
	v_mfma_f32_16x16x32_bf16 v[66:69], v[142:145], v[178:181], v[66:69]
	s_setprio 1
	s_barrier
	s_and_b64 vcc, exec, s[42:43]
	s_cbranch_vccnz .LBB0_1618
	ds_read_b128 v[174:177], v233 offset:49152
	ds_read_b128 v[190:193], v233 offset:50176
	ds_read_b128 v[170:173], v233 offset:51200
	ds_read_b128 v[186:189], v233 offset:52224
	ds_read_b128 v[166:169], v233 offset:53248
	ds_read_b128 v[182:185], v233 offset:54272
	ds_read_b128 v[162:165], v233 offset:55296
	ds_read_b128 v[178:181], v233 offset:56320
.LBB0_1618:
	s_add_u32 s56, s50, 0x40000
	s_addc_u32 s57, s51, 0
	s_add_u32 s52, s52, 0x220000
	s_addc_u32 s53, s53, 0
	s_mov_b32 m0, s17
	s_add_u32 s50, s50, 0x44000
	global_load_lds_dwordx4 v194, s[56:57]
	s_mov_b32 m0, s29
	s_addc_u32 s51, s51, 0
	global_load_lds_dwordx4 v196, s[56:57]
	s_mov_b32 m0, s58
	s_and_b64 vcc, exec, s[42:43]
	global_load_lds_dwordx4 v194, s[50:51]
	s_mov_b32 m0, s59
	s_nop 0
	global_load_lds_dwordx4 v196, s[50:51]
	s_mov_b64 s[100:101], s[52:53]
	s_waitcnt vmcnt(6)
	s_waitcnt lgkmcnt(0)
	s_barrier
	s_cbranch_vccnz .LBB0_1611
	s_setprio 0
	s_waitcnt lgkmcnt(0)
	v_mfma_f32_16x16x32_bf16 v[62:65], v[146:149], v[174:177], v[62:65]
	v_mfma_f32_16x16x32_bf16 v[58:61], v[154:157], v[174:177], v[58:61]
	v_mfma_f32_16x16x32_bf16 v[46:49], v[146:149], v[170:173], v[46:49]
	v_mfma_f32_16x16x32_bf16 v[42:45], v[154:157], v[170:173], v[42:45]
	v_mfma_f32_16x16x32_bf16 v[30:33], v[146:149], v[166:169], v[30:33]
	v_mfma_f32_16x16x32_bf16 v[26:29], v[154:157], v[166:169], v[26:29]
	v_mfma_f32_16x16x32_bf16 v[14:17], v[146:149], v[162:165], v[14:17]
	v_mfma_f32_16x16x32_bf16 v[10:13], v[154:157], v[162:165], v[10:13]
	v_mfma_f32_16x16x32_bf16 v[62:65], v[150:153], v[190:193], v[62:65]
	v_mfma_f32_16x16x32_bf16 v[58:61], v[158:161], v[190:193], v[58:61]
	v_mfma_f32_16x16x32_bf16 v[46:49], v[150:153], v[186:189], v[46:49]
	v_mfma_f32_16x16x32_bf16 v[42:45], v[158:161], v[186:189], v[42:45]
	v_mfma_f32_16x16x32_bf16 v[30:33], v[150:153], v[182:185], v[30:33]
	v_mfma_f32_16x16x32_bf16 v[26:29], v[158:161], v[182:185], v[26:29]
	v_mfma_f32_16x16x32_bf16 v[14:17], v[150:153], v[178:181], v[14:17]
	v_mfma_f32_16x16x32_bf16 v[10:13], v[158:161], v[178:181], v[10:13]
	s_setprio 1
	s_setprio 0
	v_mfma_f32_16x16x32_bf16 v[54:57], v[130:133], v[174:177], v[54:57]
	v_mfma_f32_16x16x32_bf16 v[50:53], v[138:141], v[174:177], v[50:53]
	v_mfma_f32_16x16x32_bf16 v[38:41], v[130:133], v[170:173], v[38:41]
	v_mfma_f32_16x16x32_bf16 v[34:37], v[138:141], v[170:173], v[34:37]
	v_mfma_f32_16x16x32_bf16 v[22:25], v[130:133], v[166:169], v[22:25]
	v_mfma_f32_16x16x32_bf16 v[18:21], v[138:141], v[166:169], v[18:21]
	v_mfma_f32_16x16x32_bf16 v[6:9], v[130:133], v[162:165], v[6:9]
	v_mfma_f32_16x16x32_bf16 v[2:5], v[138:141], v[162:165], v[2:5]
	v_mfma_f32_16x16x32_bf16 v[54:57], v[134:137], v[190:193], v[54:57]
	v_mfma_f32_16x16x32_bf16 v[50:53], v[142:145], v[190:193], v[50:53]
	v_mfma_f32_16x16x32_bf16 v[38:41], v[134:137], v[186:189], v[38:41]
	v_mfma_f32_16x16x32_bf16 v[34:37], v[142:145], v[186:189], v[34:37]
	v_mfma_f32_16x16x32_bf16 v[22:25], v[134:137], v[182:185], v[22:25]
	v_mfma_f32_16x16x32_bf16 v[18:21], v[142:145], v[182:185], v[18:21]
	v_mfma_f32_16x16x32_bf16 v[6:9], v[134:137], v[178:181], v[6:9]
	v_mfma_f32_16x16x32_bf16 v[2:5], v[142:145], v[178:181], v[2:5]
	s_setprio 1
	s_branch .LBB0_1611
